# GLA recurrence hand-written compact loop (2 operand sets in flight, no rotation moves); LRU scan with next-8-step LDS reads in flight
# speedup vs baseline: 1.0170x; 1.0170x over previous
; #define LAS __attribute__((address_space(3)))
; __device__ __forceinline__ float sigmoidf_(float x) { return __builtin_amdgcn_rcpf(1.f + __expf(-x)); }
; __device__ __forceinline__ void lru_job(const bf16_t* P, bf16_t* Y, int l, int b, int kb, LAS float* lds, int wave_s) {
;     ...
;         for (int tt = 0; tt < 8; ++tt) { const int t = tg * 8 + tt; f32x2_t dd = {ba, bx};
; #pragma unroll
;             for (int i4 = 0; i4 < 16; ++i4) { const f32x4 xv = *(const LAS f32x4*)(XC + t * 64 + 4 * i4);
; #pragma unroll
;                 for (int q = 0; q < 4; ++q) { const f32x2_t xb = {xv[q], xv[q]}; dd = __builtin_elementwise_fma(xb, wax[4 * i4 + q], dd); } }
;             const float rg = sigmoidf_(dd.x), ig = sigmoidf_(dd.y);
;             const float la = -8.f * rg * spl;
;             const float av = __expf(la);
;             Aa[t * 64 + j] = av;
;             Uu[t * 64 + j] = sqrtf(fmaxf(1.f - av * av, 0.f)) * (ig * XC[t * 64 + j]); }
.LBB0_242:
	ds_read_b128 v[40:43], v99
	ds_read_b128 v[56:59], v99 offset:4096
	ds_read_b128 v[44:47], v99 offset:16
	ds_read_b128 v[60:63], v99 offset:4112
	ds_read_b128 v[48:51], v99 offset:32
	ds_read_b128 v[64:67], v99 offset:4128
	ds_read_b128 v[52:55], v99 offset:48
	ds_read_b128 v[68:71], v99 offset:4144
	ds_read_b32 v88, v100
	ds_read_b32 v89, v100 offset:256
	ds_read_b32 v90, v100 offset:512
	ds_read_b32 v91, v100 offset:768
	ds_read_b32 v92, v100 offset:4096
	ds_read_b32 v93, v100 offset:4352
	ds_read_b32 v94, v100 offset:4608
	ds_read_b32 v95, v100 offset:4864
	v_mov_b32_e32 v72, v96
	v_mov_b32_e32 v73, v96
	v_mov_b32_e32 v74, v96
	v_mov_b32_e32 v75, v96
	v_mov_b32_e32 v76, v97
	v_mov_b32_e32 v77, v97
	v_mov_b32_e32 v78, v97
	v_mov_b32_e32 v79, v97
	v_mov_b32_e32 v80, v96
	v_mov_b32_e32 v81, v96
	v_mov_b32_e32 v82, v96
	v_mov_b32_e32 v83, v96
	v_mov_b32_e32 v84, v97
	v_mov_b32_e32 v85, v97
	v_mov_b32_e32 v86, v97
	v_mov_b32_e32 v87, v97
	s_waitcnt lgkmcnt(14)
	s_nop 1
	v_mfma_f32_16x16x4_f32 v[72:75], v40, v0, v[72:75]
	v_mfma_f32_16x16x4_f32 v[76:79], v40, v16, v[76:79]
	v_mfma_f32_16x16x4_f32 v[80:83], v56, v0, v[80:83]
	v_mfma_f32_16x16x4_f32 v[84:87], v56, v16, v[84:87]
	v_mfma_f32_16x16x4_f32 v[72:75], v41, v1, v[72:75]
	v_mfma_f32_16x16x4_f32 v[76:79], v41, v17, v[76:79]
	v_mfma_f32_16x16x4_f32 v[80:83], v57, v1, v[80:83]
	v_mfma_f32_16x16x4_f32 v[84:87], v57, v17, v[84:87]
	v_mfma_f32_16x16x4_f32 v[72:75], v42, v2, v[72:75]
	v_mfma_f32_16x16x4_f32 v[76:79], v42, v18, v[76:79]
	v_mfma_f32_16x16x4_f32 v[80:83], v58, v2, v[80:83]
	v_mfma_f32_16x16x4_f32 v[84:87], v58, v18, v[84:87]
	v_mfma_f32_16x16x4_f32 v[72:75], v43, v3, v[72:75]
	v_mfma_f32_16x16x4_f32 v[76:79], v43, v19, v[76:79]
	v_mfma_f32_16x16x4_f32 v[80:83], v59, v3, v[80:83]
	v_mfma_f32_16x16x4_f32 v[84:87], v59, v19, v[84:87]
	s_waitcnt lgkmcnt(12)
	v_mfma_f32_16x16x4_f32 v[72:75], v44, v4, v[72:75]
	v_mfma_f32_16x16x4_f32 v[76:79], v44, v20, v[76:79]
	v_mfma_f32_16x16x4_f32 v[80:83], v60, v4, v[80:83]
	v_mfma_f32_16x16x4_f32 v[84:87], v60, v20, v[84:87]
	v_mfma_f32_16x16x4_f32 v[72:75], v45, v5, v[72:75]
	v_mfma_f32_16x16x4_f32 v[76:79], v45, v21, v[76:79]
	v_mfma_f32_16x16x4_f32 v[80:83], v61, v5, v[80:83]
	v_mfma_f32_16x16x4_f32 v[84:87], v61, v21, v[84:87]
	v_mfma_f32_16x16x4_f32 v[72:75], v46, v6, v[72:75]
	v_mfma_f32_16x16x4_f32 v[76:79], v46, v22, v[76:79]
	v_mfma_f32_16x16x4_f32 v[80:83], v62, v6, v[80:83]
	v_mfma_f32_16x16x4_f32 v[84:87], v62, v22, v[84:87]
	v_mfma_f32_16x16x4_f32 v[72:75], v47, v7, v[72:75]
	v_mfma_f32_16x16x4_f32 v[76:79], v47, v23, v[76:79]
	v_mfma_f32_16x16x4_f32 v[80:83], v63, v7, v[80:83]
	v_mfma_f32_16x16x4_f32 v[84:87], v63, v23, v[84:87]
	s_waitcnt lgkmcnt(10)
	v_mfma_f32_16x16x4_f32 v[72:75], v48, v8, v[72:75]
	v_mfma_f32_16x16x4_f32 v[76:79], v48, v24, v[76:79]
	v_mfma_f32_16x16x4_f32 v[80:83], v64, v8, v[80:83]
	v_mfma_f32_16x16x4_f32 v[84:87], v64, v24, v[84:87]
	v_mfma_f32_16x16x4_f32 v[72:75], v49, v9, v[72:75]
	v_mfma_f32_16x16x4_f32 v[76:79], v49, v25, v[76:79]
	v_mfma_f32_16x16x4_f32 v[80:83], v65, v9, v[80:83]
	v_mfma_f32_16x16x4_f32 v[84:87], v65, v25, v[84:87]
	v_mfma_f32_16x16x4_f32 v[72:75], v50, v10, v[72:75]
	v_mfma_f32_16x16x4_f32 v[76:79], v50, v26, v[76:79]
	v_mfma_f32_16x16x4_f32 v[80:83], v66, v10, v[80:83]
	v_mfma_f32_16x16x4_f32 v[84:87], v66, v26, v[84:87]
	v_mfma_f32_16x16x4_f32 v[72:75], v51, v11, v[72:75]
	v_mfma_f32_16x16x4_f32 v[76:79], v51, v27, v[76:79]
	v_mfma_f32_16x16x4_f32 v[80:83], v67, v11, v[80:83]
	v_mfma_f32_16x16x4_f32 v[84:87], v67, v27, v[84:87]
	s_waitcnt lgkmcnt(8)
	v_mfma_f32_16x16x4_f32 v[72:75], v52, v12, v[72:75]
	v_mfma_f32_16x16x4_f32 v[76:79], v52, v28, v[76:79]
	v_mfma_f32_16x16x4_f32 v[80:83], v68, v12, v[80:83]
	v_mfma_f32_16x16x4_f32 v[84:87], v68, v28, v[84:87]
	v_mfma_f32_16x16x4_f32 v[72:75], v53, v13, v[72:75]
	v_mfma_f32_16x16x4_f32 v[76:79], v53, v29, v[76:79]
	v_mfma_f32_16x16x4_f32 v[80:83], v69, v13, v[80:83]
	v_mfma_f32_16x16x4_f32 v[84:87], v69, v29, v[84:87]
	v_mfma_f32_16x16x4_f32 v[72:75], v54, v14, v[72:75]
	v_mfma_f32_16x16x4_f32 v[76:79], v54, v30, v[76:79]
	v_mfma_f32_16x16x4_f32 v[80:83], v70, v14, v[80:83]
	v_mfma_f32_16x16x4_f32 v[84:87], v70, v30, v[84:87]
	v_mfma_f32_16x16x4_f32 v[72:75], v55, v15, v[72:75]
	v_mfma_f32_16x16x4_f32 v[76:79], v55, v31, v[76:79]
	v_mfma_f32_16x16x4_f32 v[80:83], v71, v15, v[80:83]
	v_mfma_f32_16x16x4_f32 v[84:87], v71, v31, v[84:87]
	s_waitcnt lgkmcnt(0)
; __device__ __forceinline__ float sigmoidf_(float x) { return __builtin_amdgcn_rcpf(1.f + __expf(-x)); }
; __device__ __forceinline__ void lru_job(const bf16_t* P, bf16_t* Y, int l, int b, int kb, LAS float* lds, int wave_s) {
;     ...
;             const float rg = sigmoidf_(dd.x), ig = sigmoidf_(dd.y);
;             const float la = -8.f * rg * spl;
;             const float av = __expf(la);
;             Aa[t * 64 + j] = av;
;             Uu[t * 64 + j] = sqrtf(fmaxf(1.f - av * av, 0.f)) * (ig * XC[t * 64 + j]); }
;         __syncthreads();
;         if (tid < 64) {
	s_nop 7
	s_nop 3
	v_mul_f32_e32 v101, 0xbfb8aa3b, v72
	v_mul_f32_e32 v104, 0xbfb8aa3b, v73
	v_exp_f32_e32 v101, v101
	v_exp_f32_e32 v104, v104
	v_mul_f32_e32 v102, 0xbfb8aa3b, v76
	v_mul_f32_e32 v105, 0xbfb8aa3b, v77
	v_exp_f32_e32 v102, v102
	v_exp_f32_e32 v105, v105
	v_add_f32_e32 v101, 1.0, v101
	v_add_f32_e32 v104, 1.0, v104
	v_rcp_f32_e32 v101, v101
	v_rcp_f32_e32 v104, v104
	v_add_f32_e32 v102, 1.0, v102
	v_add_f32_e32 v105, 1.0, v105
	v_rcp_f32_e32 v102, v102
	v_rcp_f32_e32 v105, v105
	v_mul_f32_e32 v101, 0xc1000000, v101
	v_mul_f32_e32 v104, 0xc1000000, v104
	v_mul_f32_e32 v101, v98, v101
	v_mul_f32_e32 v104, v98, v104
	v_mul_f32_e32 v101, 0x3fb8aa3b, v101
	v_mul_f32_e32 v104, 0x3fb8aa3b, v104
	v_exp_f32_e32 v101, v101
	v_exp_f32_e32 v104, v104
	v_mul_f32_e32 v102, v88, v102
	v_mul_f32_e32 v105, v89, v105
	v_fma_f32 v103, -v101, v101, 1.0
	v_fma_f32 v106, -v104, v104, 1.0
	v_max_f32_e32 v103, 0, v103
	v_max_f32_e32 v106, 0, v106
	v_sqrt_f32_e32 v103, v103
	v_sqrt_f32_e32 v106, v106
	s_nop 0
	s_nop 0
	v_mul_f32_e32 v102, v102, v103
	v_mul_f32_e32 v105, v105, v106
	ds_write2st64_b32 v100, v101, v102 offset0:64 offset1:128
	ds_write2st64_b32 v100, v104, v105 offset0:65 offset1:129
	v_mul_f32_e32 v101, 0xbfb8aa3b, v74
	v_mul_f32_e32 v104, 0xbfb8aa3b, v75
	v_exp_f32_e32 v101, v101
	v_exp_f32_e32 v104, v104
	v_mul_f32_e32 v102, 0xbfb8aa3b, v78
	v_mul_f32_e32 v105, 0xbfb8aa3b, v79
	v_exp_f32_e32 v102, v102
	v_exp_f32_e32 v105, v105
	v_add_f32_e32 v101, 1.0, v101
	v_add_f32_e32 v104, 1.0, v104
	v_rcp_f32_e32 v101, v101
	v_rcp_f32_e32 v104, v104
	v_add_f32_e32 v102, 1.0, v102
	v_add_f32_e32 v105, 1.0, v105
	v_rcp_f32_e32 v102, v102
	v_rcp_f32_e32 v105, v105
	v_mul_f32_e32 v101, 0xc1000000, v101
	v_mul_f32_e32 v104, 0xc1000000, v104
	v_mul_f32_e32 v101, v98, v101
	v_mul_f32_e32 v104, v98, v104
	v_mul_f32_e32 v101, 0x3fb8aa3b, v101
	v_mul_f32_e32 v104, 0x3fb8aa3b, v104
	v_exp_f32_e32 v101, v101
	v_exp_f32_e32 v104, v104
	v_mul_f32_e32 v102, v90, v102
	v_mul_f32_e32 v105, v91, v105
	v_fma_f32 v103, -v101, v101, 1.0
	v_fma_f32 v106, -v104, v104, 1.0
	v_max_f32_e32 v103, 0, v103
	v_max_f32_e32 v106, 0, v106
	v_sqrt_f32_e32 v103, v103
	v_sqrt_f32_e32 v106, v106
	s_nop 0
	s_nop 0
	v_mul_f32_e32 v102, v102, v103
	v_mul_f32_e32 v105, v105, v106
	ds_write2st64_b32 v100, v101, v102 offset0:66 offset1:130
	ds_write2st64_b32 v100, v104, v105 offset0:67 offset1:131
	v_mul_f32_e32 v101, 0xbfb8aa3b, v80
	v_mul_f32_e32 v104, 0xbfb8aa3b, v81
	v_exp_f32_e32 v101, v101
	v_exp_f32_e32 v104, v104
	v_mul_f32_e32 v102, 0xbfb8aa3b, v84
	v_mul_f32_e32 v105, 0xbfb8aa3b, v85
	v_exp_f32_e32 v102, v102
	v_exp_f32_e32 v105, v105
	v_add_f32_e32 v101, 1.0, v101
	v_add_f32_e32 v104, 1.0, v104
	v_rcp_f32_e32 v101, v101
	v_rcp_f32_e32 v104, v104
	v_add_f32_e32 v102, 1.0, v102
	v_add_f32_e32 v105, 1.0, v105
	v_rcp_f32_e32 v102, v102
	v_rcp_f32_e32 v105, v105
	v_mul_f32_e32 v101, 0xc1000000, v101
	v_mul_f32_e32 v104, 0xc1000000, v104
	v_mul_f32_e32 v101, v98, v101
	v_mul_f32_e32 v104, v98, v104
	v_mul_f32_e32 v101, 0x3fb8aa3b, v101
	v_mul_f32_e32 v104, 0x3fb8aa3b, v104
	v_exp_f32_e32 v101, v101
	v_exp_f32_e32 v104, v104
	v_mul_f32_e32 v102, v92, v102
	v_mul_f32_e32 v105, v93, v105
	v_fma_f32 v103, -v101, v101, 1.0
	v_fma_f32 v106, -v104, v104, 1.0
	v_max_f32_e32 v103, 0, v103
	v_max_f32_e32 v106, 0, v106
	v_sqrt_f32_e32 v103, v103
	v_sqrt_f32_e32 v106, v106
	s_nop 0
	s_nop 0
	v_mul_f32_e32 v102, v102, v103
	v_mul_f32_e32 v105, v105, v106
	ds_write2st64_b32 v100, v101, v102 offset0:80 offset1:144
	ds_write2st64_b32 v100, v104, v105 offset0:81 offset1:145
	v_mul_f32_e32 v101, 0xbfb8aa3b, v82
	v_mul_f32_e32 v104, 0xbfb8aa3b, v83
	v_exp_f32_e32 v101, v101
	v_exp_f32_e32 v104, v104
	v_mul_f32_e32 v102, 0xbfb8aa3b, v86
	v_mul_f32_e32 v105, 0xbfb8aa3b, v87
	v_exp_f32_e32 v102, v102
	v_exp_f32_e32 v105, v105
	v_add_f32_e32 v101, 1.0, v101
	v_add_f32_e32 v104, 1.0, v104
	v_rcp_f32_e32 v101, v101
	v_rcp_f32_e32 v104, v104
	v_add_f32_e32 v102, 1.0, v102
	v_add_f32_e32 v105, 1.0, v105
	v_rcp_f32_e32 v102, v102
	v_rcp_f32_e32 v105, v105
	v_mul_f32_e32 v101, 0xc1000000, v101
	v_mul_f32_e32 v104, 0xc1000000, v104
	v_mul_f32_e32 v101, v98, v101
	v_mul_f32_e32 v104, v98, v104
	v_mul_f32_e32 v101, 0x3fb8aa3b, v101
	v_mul_f32_e32 v104, 0x3fb8aa3b, v104
	v_exp_f32_e32 v101, v101
	v_exp_f32_e32 v104, v104
	v_mul_f32_e32 v102, v94, v102
	v_mul_f32_e32 v105, v95, v105
	v_fma_f32 v103, -v101, v101, 1.0
	v_fma_f32 v106, -v104, v104, 1.0
	v_max_f32_e32 v103, 0, v103
	v_max_f32_e32 v106, 0, v106
	v_sqrt_f32_e32 v103, v103
	v_sqrt_f32_e32 v106, v106
	s_nop 0
	s_nop 0
	v_mul_f32_e32 v102, v102, v103
	v_mul_f32_e32 v105, v105, v106
	ds_write2st64_b32 v100, v101, v102 offset0:82 offset1:146
	ds_write2st64_b32 v100, v104, v105 offset0:83 offset1:147
	s_waitcnt lgkmcnt(0)
	s_barrier
	s_and_saveexec_b64 s[4:5], vcc
	s_cbranch_execz .LBB0_239
; __device__ __forceinline__ void lru_job(const bf16_t* P, bf16_t* Y, int l, int b, int kb, LAS float* lds, int wave_s) {
;     ...
;         if (tid < 64) {
;             for (int tb = 0; tb < TC; tb += 8) { float av[8], uv[8];
; #pragma unroll
;                 for (int k = 0; k < 8; ++k) { av[k] = Aa[(tb + k) * 64 + j]; uv[k] = Uu[(tb + k) * 64 + j]; }
; #pragma unroll
;                 for (int k = 0; k < 8; ++k) { hs = av[k] * hs + uv[k]; Hh[(tb + k) * 64 + j] = hs; } }
;         }
	ds_read2st64_b32 v[216:217], v177 offset0:64 offset1:65
	ds_read2st64_b32 v[218:219], v177 offset0:66 offset1:67
	ds_read2st64_b32 v[220:221], v177 offset0:68 offset1:69
	ds_read2st64_b32 v[222:223], v177 offset0:70 offset1:71
	ds_read2st64_b32 v[224:225], v177 offset0:128 offset1:129
	ds_read2st64_b32 v[226:227], v177 offset0:130 offset1:131
	ds_read2st64_b32 v[228:229], v177 offset0:132 offset1:133
	ds_read2st64_b32 v[230:231], v177 offset0:134 offset1:135
	ds_read2st64_b32 v[234:235], v177 offset0:72 offset1:73
	ds_read2st64_b32 v[236:237], v177 offset0:74 offset1:75
	ds_read2st64_b32 v[238:239], v177 offset0:76 offset1:77
	ds_read2st64_b32 v[240:241], v177 offset0:78 offset1:79
	ds_read2st64_b32 v[242:243], v177 offset0:136 offset1:137
	ds_read2st64_b32 v[244:245], v177 offset0:138 offset1:139
	ds_read2st64_b32 v[246:247], v177 offset0:140 offset1:141
	ds_read2st64_b32 v[248:249], v177 offset0:142 offset1:143
	s_waitcnt lgkmcnt(8)
	v_fmac_f32_e32 v224, v135, v216
	v_fmac_f32_e32 v225, v224, v217
	v_fmac_f32_e32 v226, v225, v218
	v_fmac_f32_e32 v227, v226, v219
	v_fmac_f32_e32 v228, v227, v220
	v_fmac_f32_e32 v229, v228, v221
	v_fmac_f32_e32 v230, v229, v222
	v_fmac_f32_e32 v231, v230, v223
	ds_write2st64_b32 v177, v224, v225 offset0:192 offset1:193
	ds_write2st64_b32 v177, v226, v227 offset0:194 offset1:195
	ds_write2st64_b32 v177, v228, v229 offset0:196 offset1:197
	ds_write2st64_b32 v177, v230, v231 offset0:198 offset1:199
	ds_read2st64_b32 v[216:217], v177 offset0:80 offset1:81
	ds_read2st64_b32 v[218:219], v177 offset0:82 offset1:83
	ds_read2st64_b32 v[220:221], v177 offset0:84 offset1:85
	ds_read2st64_b32 v[222:223], v177 offset0:86 offset1:87
	ds_read2st64_b32 v[224:225], v177 offset0:144 offset1:145
	ds_read2st64_b32 v[226:227], v177 offset0:146 offset1:147
	ds_read2st64_b32 v[228:229], v177 offset0:148 offset1:149
	ds_read2st64_b32 v[230:231], v177 offset0:150 offset1:151
	s_waitcnt lgkmcnt(12)
	v_fmac_f32_e32 v242, v231, v234
	v_fmac_f32_e32 v243, v242, v235
	v_fmac_f32_e32 v244, v243, v236
	v_fmac_f32_e32 v245, v244, v237
	v_fmac_f32_e32 v246, v245, v238
	v_fmac_f32_e32 v247, v246, v239
	v_fmac_f32_e32 v248, v247, v240
	v_fmac_f32_e32 v249, v248, v241
	ds_write2st64_b32 v177, v242, v243 offset0:200 offset1:201
	ds_write2st64_b32 v177, v244, v245 offset0:202 offset1:203
	ds_write2st64_b32 v177, v246, v247 offset0:204 offset1:205
	ds_write2st64_b32 v177, v248, v249 offset0:206 offset1:207
	ds_read2st64_b32 v[234:235], v177 offset0:88 offset1:89
	ds_read2st64_b32 v[236:237], v177 offset0:90 offset1:91
	ds_read2st64_b32 v[238:239], v177 offset0:92 offset1:93
	ds_read2st64_b32 v[240:241], v177 offset0:94 offset1:95
	ds_read2st64_b32 v[242:243], v177 offset0:152 offset1:153
	ds_read2st64_b32 v[244:245], v177 offset0:154 offset1:155
	ds_read2st64_b32 v[246:247], v177 offset0:156 offset1:157
	ds_read2st64_b32 v[248:249], v177 offset0:158 offset1:159
	s_waitcnt lgkmcnt(12)
	v_fmac_f32_e32 v224, v249, v216
	v_fmac_f32_e32 v225, v224, v217
	v_fmac_f32_e32 v226, v225, v218
	v_fmac_f32_e32 v227, v226, v219
	v_fmac_f32_e32 v228, v227, v220
	v_fmac_f32_e32 v229, v228, v221
	v_fmac_f32_e32 v230, v229, v222
	v_fmac_f32_e32 v231, v230, v223
	ds_write2st64_b32 v177, v224, v225 offset0:208 offset1:209
	ds_write2st64_b32 v177, v226, v227 offset0:210 offset1:211
	ds_write2st64_b32 v177, v228, v229 offset0:212 offset1:213
	ds_write2st64_b32 v177, v230, v231 offset0:214 offset1:215
	ds_read2st64_b32 v[216:217], v177 offset0:96 offset1:97
	ds_read2st64_b32 v[218:219], v177 offset0:98 offset1:99
	ds_read2st64_b32 v[220:221], v177 offset0:100 offset1:101
	ds_read2st64_b32 v[222:223], v177 offset0:102 offset1:103
	ds_read2st64_b32 v[224:225], v177 offset0:160 offset1:161
	ds_read2st64_b32 v[226:227], v177 offset0:162 offset1:163
	ds_read2st64_b32 v[228:229], v177 offset0:164 offset1:165
	ds_read2st64_b32 v[230:231], v177 offset0:166 offset1:167
	s_waitcnt lgkmcnt(12)
; __device__ __forceinline__ void lru_job(const bf16_t* P, bf16_t* Y, int l, int b, int kb, LAS float* lds, int wave_s) {
;     ...
;         if (tid < 64) {
;             for (int tb = 0; tb < TC; tb += 8) { float av[8], uv[8];
; #pragma unroll
;                 for (int k = 0; k < 8; ++k) { av[k] = Aa[(tb + k) * 64 + j]; uv[k] = Uu[(tb + k) * 64 + j]; }
; #pragma unroll
;                 for (int k = 0; k < 8; ++k) { hs = av[k] * hs + uv[k]; Hh[(tb + k) * 64 + j] = hs; } }
;         }
	v_fmac_f32_e32 v242, v231, v234
	v_fmac_f32_e32 v243, v242, v235
	v_fmac_f32_e32 v244, v243, v236
	v_fmac_f32_e32 v245, v244, v237
	v_fmac_f32_e32 v246, v245, v238
	v_fmac_f32_e32 v247, v246, v239
	v_fmac_f32_e32 v248, v247, v240
	v_fmac_f32_e32 v249, v248, v241
	ds_write2st64_b32 v177, v242, v243 offset0:216 offset1:217
	ds_write2st64_b32 v177, v244, v245 offset0:218 offset1:219
	ds_write2st64_b32 v177, v246, v247 offset0:220 offset1:221
	ds_write2st64_b32 v177, v248, v249 offset0:222 offset1:223
	ds_read2st64_b32 v[234:235], v177 offset0:104 offset1:105
	ds_read2st64_b32 v[236:237], v177 offset0:106 offset1:107
	ds_read2st64_b32 v[238:239], v177 offset0:108 offset1:109
	ds_read2st64_b32 v[240:241], v177 offset0:110 offset1:111
	ds_read2st64_b32 v[242:243], v177 offset0:168 offset1:169
	ds_read2st64_b32 v[244:245], v177 offset0:170 offset1:171
	ds_read2st64_b32 v[246:247], v177 offset0:172 offset1:173
	ds_read2st64_b32 v[248:249], v177 offset0:174 offset1:175
	s_waitcnt lgkmcnt(12)
	v_fmac_f32_e32 v224, v249, v216
	v_fmac_f32_e32 v225, v224, v217
	v_fmac_f32_e32 v226, v225, v218
	v_fmac_f32_e32 v227, v226, v219
	v_fmac_f32_e32 v228, v227, v220
	v_fmac_f32_e32 v229, v228, v221
	v_fmac_f32_e32 v230, v229, v222
	v_fmac_f32_e32 v231, v230, v223
	ds_write2st64_b32 v177, v224, v225 offset0:224 offset1:225
	ds_write2st64_b32 v177, v226, v227 offset0:226 offset1:227
	ds_write2st64_b32 v177, v228, v229 offset0:228 offset1:229
	ds_write2st64_b32 v177, v230, v231 offset0:230 offset1:231
	ds_read2st64_b32 v[216:217], v177 offset0:112 offset1:113
	ds_read2st64_b32 v[218:219], v177 offset0:114 offset1:115
	ds_read2st64_b32 v[220:221], v177 offset0:116 offset1:117
	ds_read2st64_b32 v[222:223], v177 offset0:118 offset1:119
	ds_read2st64_b32 v[224:225], v177 offset0:176 offset1:177
	ds_read2st64_b32 v[226:227], v177 offset0:178 offset1:179
	ds_read2st64_b32 v[228:229], v177 offset0:180 offset1:181
	ds_read2st64_b32 v[230:231], v177 offset0:182 offset1:183
	s_waitcnt lgkmcnt(12)
	v_fmac_f32_e32 v242, v231, v234
	v_fmac_f32_e32 v243, v242, v235
	v_fmac_f32_e32 v244, v243, v236
	v_fmac_f32_e32 v245, v244, v237
	v_fmac_f32_e32 v246, v245, v238
	v_fmac_f32_e32 v247, v246, v239
	v_fmac_f32_e32 v248, v247, v240
	v_fmac_f32_e32 v249, v248, v241
	ds_write2st64_b32 v177, v242, v243 offset0:232 offset1:233
	ds_write2st64_b32 v177, v244, v245 offset0:234 offset1:235
	ds_write2st64_b32 v177, v246, v247 offset0:236 offset1:237
	ds_write2st64_b32 v177, v248, v249 offset0:238 offset1:239
	ds_read2st64_b32 v[234:235], v177 offset0:120 offset1:121
	ds_read2st64_b32 v[236:237], v177 offset0:122 offset1:123
	ds_read2st64_b32 v[238:239], v177 offset0:124 offset1:125
	ds_read2st64_b32 v[240:241], v177 offset0:126 offset1:127
	ds_read2st64_b32 v[242:243], v177 offset0:184 offset1:185
	ds_read2st64_b32 v[244:245], v177 offset0:186 offset1:187
	ds_read2st64_b32 v[246:247], v177 offset0:188 offset1:189
	ds_read2st64_b32 v[248:249], v177 offset0:190 offset1:191
	s_waitcnt lgkmcnt(12)
	v_fmac_f32_e32 v224, v249, v216
	v_fmac_f32_e32 v225, v224, v217
	v_fmac_f32_e32 v226, v225, v218
	v_fmac_f32_e32 v227, v226, v219
	v_fmac_f32_e32 v228, v227, v220
	v_fmac_f32_e32 v229, v228, v221
	v_fmac_f32_e32 v230, v229, v222
	v_fmac_f32_e32 v231, v230, v223
	ds_write2st64_b32 v177, v224, v225 offset0:240 offset1:241
	ds_write2st64_b32 v177, v226, v227 offset0:242 offset1:243
	ds_write2st64_b32 v177, v228, v229 offset0:244 offset1:245
	ds_write2st64_b32 v177, v230, v231 offset0:246 offset1:247
	s_waitcnt lgkmcnt(4)
	v_fmac_f32_e32 v242, v231, v234
	v_fmac_f32_e32 v243, v242, v235
	v_fmac_f32_e32 v244, v243, v236
	v_fmac_f32_e32 v245, v244, v237
	v_fmac_f32_e32 v246, v245, v238
	v_fmac_f32_e32 v247, v246, v239
	v_fmac_f32_e32 v248, v247, v240
	v_fmac_f32_e32 v249, v248, v241
	ds_write2st64_b32 v177, v242, v243 offset0:248 offset1:249
	ds_write2st64_b32 v177, v244, v245 offset0:250 offset1:251
	ds_write2st64_b32 v177, v246, v247 offset0:252 offset1:253
	ds_write2st64_b32 v177, v248, v249 offset0:254 offset1:255
	v_mov_b32_e32 v135, v249
	s_branch .LBB0_239

; #define LAS __attribute__((address_space(3)))
; #define GLA_LD(t_, aq, kq, qq, vq) do { const int tt_ = (t_); vq = Bs[6144 + tt_ * 64 + pp]; \
;             _Pragma("unroll") for (int u = 0; u < 2; ++u) { aq[u] = *(const LAS f32x4*)(Bs + 4096 + tt_ * 32 + k0 + 4 * u); kq[u] = *(const LAS f32x4*)(Bs + 2048 + tt_ * 32 + k0 + 4 * u); qq[u] = *(const LAS f32x4*)(Bs + tt_ * 32 + k0 + 4 * u); } } while (0)
; #define GLA_STEP(t_, aq, kq, qq, vq) do { float y = 0.f; \
;             _Pragma("unroll") for (int u = 0; u < 2; ++u) _Pragma("unroll") for (int j = 0; j < 4; ++j) { S[4 * u + j] = aq[u][j] * S[4 * u + j] + kq[u][j] * vq; y += qq[u][j] * S[4 * u + j]; } \
;             y += dpp_f(y, 0xB1); y += dpp_f(y, 0x4E); ydst[(t_) * ystride] = y; } while (0)
; __device__ __forceinline__ void gla_job(const bf16_t* P, bf16_t* Y, int l, int b, int h, LAS float* lds, int wave_s) {
;     ...
;         if (wave_s < 4) {
;             LAS float* ydst = (lane & 3) == 0 ? (Yl + (c & 1) * 4096 + pp) : (lds + (LDS_XB + 256) / 4 + lane); const int ystride = (lane & 3) == 0 ? 64 : 0;
;             f32x4 a0_[2], k0_[2], q0_[2], a1_[2], k1_[2], q1_[2]; float v0_, v1_;
;     ...
;             GLA_LD(0, a0_, k0_, q0_, v0_);
;             for (int t = 0; t < TC; t += 2) {
;                 GLA_LD(t + 1, a1_, k1_, q1_, v1_);
;                 GLA_STEP(t, a0_, k0_, q0_, v0_);
;                 GLA_LD(t + 2 < TC ? t + 2 : t + 1, a0_, k0_, q0_, v0_);
;                 GLA_STEP(t + 1, a1_, k1_, q1_, v1_);
;             }
.LBB0_332:
	s_andn2_b64 vcc, exec, s[6:7]
	s_cbranch_vccnz .LBB0_323
	s_waitcnt vmcnt(15)
	v_cndmask_b32_e64 v0, 0, 1, s[8:9]
	s_mov_b32 s6, 0xa000
	v_mul_lo_u32 v0, v0, s6
	v_lshl_add_u32 v173, v132, 2, s15
	v_add_u32_e32 v24, v163, v0
	v_add_u32_e32 v171, v164, v0
	v_lshl_add_u32 v35, s26, 14, v133
	v_lshl_add_u32 v172, v131, 2, s15
	v_cndmask_b32_e64 v174, v156, v35, s[4:5]
	v_mov_b32_e32 v24, v173
	v_mov_b32_e32 v171, v172
	s_setprio 3
	ds_read_b128 v[0:3], v24 offset:16384
	ds_read_b128 v[4:7], v24 offset:16400
	ds_read_b128 v[8:11], v24 offset:8192
	ds_read_b128 v[12:15], v24 offset:8208
	ds_read_b32 v33, v171 offset:24576
	ds_read_b128 v[16:19], v24
	ds_read_b128 v[20:23], v24 offset:16
	ds_read_b128 v[176:179], v24 offset:16512
	ds_read_b128 v[180:183], v24 offset:16528
	ds_read_b128 v[184:187], v24 offset:8320
	ds_read_b128 v[188:191], v24 offset:8336
	ds_read_b32 v200, v171 offset:24832
	ds_read_b128 v[192:195], v24 offset:128
	ds_read_b128 v[196:199], v24 offset:144
	s_waitcnt lgkmcnt(7)
	v_mul_f32_e32 v26, v0, v26
	v_mul_f32_e32 v27, v1, v27
	v_mul_f32_e32 v28, v2, v28
	v_mul_f32_e32 v29, v3, v29
	v_mul_f32_e32 v30, v4, v30
	v_mul_f32_e32 v31, v5, v31
	v_mul_f32_e32 v32, v6, v32
	v_mul_f32_e32 v34, v7, v34
	v_fmac_f32_e32 v26, v8, v33
	v_fmac_f32_e32 v27, v9, v33
	v_fmac_f32_e32 v28, v10, v33
	v_fmac_f32_e32 v29, v11, v33
	v_fmac_f32_e32 v30, v12, v33
	v_fmac_f32_e32 v31, v13, v33
	v_fmac_f32_e32 v32, v14, v33
	v_fmac_f32_e32 v34, v15, v33
	v_mul_f32_e32 v40, v16, v26
	v_mul_f32_e32 v41, v17, v27
	v_fmac_f32_e32 v40, v18, v28
	v_fmac_f32_e32 v41, v19, v29
	v_fmac_f32_e32 v40, v20, v30
	v_fmac_f32_e32 v41, v21, v31
	v_fmac_f32_e32 v40, v22, v32
	v_fmac_f32_e32 v41, v23, v34
	v_add_f32_e32 v35, v40, v41
	s_nop 1
	v_add_f32_dpp v35, v35, v35 quad_perm:[1,0,3,2] row_mask:0xf bank_mask:0xf bound_ctrl:1
	v_add_u32_e32 v24, 0x80, v24
	v_add_u32_e32 v171, 0x100, v171
	s_mov_b32 s6, 0
.Lgla_rec_334:
	ds_read_b128 v[0:3], v24 offset:16512
	ds_read_b128 v[4:7], v24 offset:16528
	ds_read_b128 v[8:11], v24 offset:8320
	ds_read_b128 v[12:15], v24 offset:8336
	ds_read_b32 v33, v171 offset:24832
	ds_read_b128 v[16:19], v24 offset:128
	ds_read_b128 v[20:23], v24 offset:144
	s_waitcnt lgkmcnt(7)
	v_mul_f32_e32 v26, v176, v26
	v_mul_f32_e32 v27, v177, v27
	v_mul_f32_e32 v28, v178, v28
	v_mul_f32_e32 v29, v179, v29
	v_mul_f32_e32 v30, v180, v30
	v_mul_f32_e32 v31, v181, v31
	v_mul_f32_e32 v32, v182, v32
	v_mul_f32_e32 v34, v183, v34
	v_add_f32_dpp v35, v35, v35 quad_perm:[2,3,0,1] row_mask:0xf bank_mask:0xf bound_ctrl:1
	ds_write_b32 v174, v35
	v_add_u32_e32 v174, v174, v161
	v_fmac_f32_e32 v26, v184, v200
	v_fmac_f32_e32 v27, v185, v200
	v_fmac_f32_e32 v28, v186, v200
	v_fmac_f32_e32 v29, v187, v200
	v_fmac_f32_e32 v30, v188, v200
	v_fmac_f32_e32 v31, v189, v200
	v_fmac_f32_e32 v32, v190, v200
	v_fmac_f32_e32 v34, v191, v200
	v_mul_f32_e32 v40, v192, v26
	v_mul_f32_e32 v41, v193, v27
	v_fmac_f32_e32 v40, v194, v28
	v_fmac_f32_e32 v41, v195, v29
	v_fmac_f32_e32 v40, v196, v30
	v_fmac_f32_e32 v41, v197, v31
	v_fmac_f32_e32 v40, v198, v32
	v_fmac_f32_e32 v41, v199, v34
	v_add_f32_e32 v35, v40, v41
	s_nop 1
	v_add_f32_dpp v35, v35, v35 quad_perm:[1,0,3,2] row_mask:0xf bank_mask:0xf bound_ctrl:1
	ds_read_b128 v[176:179], v24 offset:16640
	ds_read_b128 v[180:183], v24 offset:16656
	ds_read_b128 v[184:187], v24 offset:8448
	ds_read_b128 v[188:191], v24 offset:8464
	ds_read_b32 v200, v171 offset:25088
	ds_read_b128 v[192:195], v24 offset:256
	ds_read_b128 v[196:199], v24 offset:272
	s_waitcnt lgkmcnt(7)
	v_mul_f32_e32 v26, v0, v26
	v_mul_f32_e32 v27, v1, v27
	v_mul_f32_e32 v28, v2, v28
	v_mul_f32_e32 v29, v3, v29
	v_mul_f32_e32 v30, v4, v30
	v_mul_f32_e32 v31, v5, v31
	v_mul_f32_e32 v32, v6, v32
	v_mul_f32_e32 v34, v7, v34
	v_add_f32_dpp v35, v35, v35 quad_perm:[2,3,0,1] row_mask:0xf bank_mask:0xf bound_ctrl:1
	ds_write_b32 v174, v35
	v_add_u32_e32 v174, v174, v161
	v_fmac_f32_e32 v26, v8, v33
	v_fmac_f32_e32 v27, v9, v33
	v_fmac_f32_e32 v28, v10, v33
	v_fmac_f32_e32 v29, v11, v33
	v_fmac_f32_e32 v30, v12, v33
	v_fmac_f32_e32 v31, v13, v33
	v_fmac_f32_e32 v32, v14, v33
	v_fmac_f32_e32 v34, v15, v33
	v_mul_f32_e32 v40, v16, v26
	v_mul_f32_e32 v41, v17, v27
	v_fmac_f32_e32 v40, v18, v28
	v_fmac_f32_e32 v41, v19, v29
	v_fmac_f32_e32 v40, v20, v30
	v_fmac_f32_e32 v41, v21, v31
	v_fmac_f32_e32 v40, v22, v32
	v_fmac_f32_e32 v41, v23, v34
	v_add_f32_e32 v35, v40, v41
	s_nop 1
	v_add_f32_dpp v35, v35, v35 quad_perm:[1,0,3,2] row_mask:0xf bank_mask:0xf bound_ctrl:1
	ds_read_b128 v[0:3], v24 offset:16768
	ds_read_b128 v[4:7], v24 offset:16784
	ds_read_b128 v[8:11], v24 offset:8576
	ds_read_b128 v[12:15], v24 offset:8592
	ds_read_b32 v33, v171 offset:25344
	ds_read_b128 v[16:19], v24 offset:384
	ds_read_b128 v[20:23], v24 offset:400
	s_waitcnt lgkmcnt(7)
	v_mul_f32_e32 v26, v176, v26
	v_mul_f32_e32 v27, v177, v27
	v_mul_f32_e32 v28, v178, v28
	v_mul_f32_e32 v29, v179, v29
	v_mul_f32_e32 v30, v180, v30
	v_mul_f32_e32 v31, v181, v31
	v_mul_f32_e32 v32, v182, v32
	v_mul_f32_e32 v34, v183, v34
	v_add_f32_dpp v35, v35, v35 quad_perm:[2,3,0,1] row_mask:0xf bank_mask:0xf bound_ctrl:1
	ds_write_b32 v174, v35
	v_add_u32_e32 v174, v174, v161
	v_fmac_f32_e32 v26, v184, v200
	v_fmac_f32_e32 v27, v185, v200
	v_fmac_f32_e32 v28, v186, v200
	v_fmac_f32_e32 v29, v187, v200
	v_fmac_f32_e32 v30, v188, v200
	v_fmac_f32_e32 v31, v189, v200
	v_fmac_f32_e32 v32, v190, v200
	v_fmac_f32_e32 v34, v191, v200
	v_mul_f32_e32 v40, v192, v26
	v_mul_f32_e32 v41, v193, v27
	v_fmac_f32_e32 v40, v194, v28
	v_fmac_f32_e32 v41, v195, v29
	v_fmac_f32_e32 v40, v196, v30
	v_fmac_f32_e32 v41, v197, v31
	v_fmac_f32_e32 v40, v198, v32
	v_fmac_f32_e32 v41, v199, v34
	v_add_f32_e32 v35, v40, v41
	s_nop 1
	v_add_f32_dpp v35, v35, v35 quad_perm:[1,0,3,2] row_mask:0xf bank_mask:0xf bound_ctrl:1
	ds_read_b128 v[176:179], v24 offset:16896
	ds_read_b128 v[180:183], v24 offset:16912
	ds_read_b128 v[184:187], v24 offset:8704
	ds_read_b128 v[188:191], v24 offset:8720
	ds_read_b32 v200, v171 offset:25600
	ds_read_b128 v[192:195], v24 offset:512
	ds_read_b128 v[196:199], v24 offset:528
	s_waitcnt lgkmcnt(7)
; #define GLA_LD(t_, aq, kq, qq, vq) do { const int tt_ = (t_); vq = Bs[6144 + tt_ * 64 + pp]; \
;             _Pragma("unroll") for (int u = 0; u < 2; ++u) { aq[u] = *(const LAS f32x4*)(Bs + 4096 + tt_ * 32 + k0 + 4 * u); kq[u] = *(const LAS f32x4*)(Bs + 2048 + tt_ * 32 + k0 + 4 * u); qq[u] = *(const LAS f32x4*)(Bs + tt_ * 32 + k0 + 4 * u); } } while (0)
; #define GLA_STEP(t_, aq, kq, qq, vq) do { float y = 0.f; \
;             _Pragma("unroll") for (int u = 0; u < 2; ++u) _Pragma("unroll") for (int j = 0; j < 4; ++j) { S[4 * u + j] = aq[u][j] * S[4 * u + j] + kq[u][j] * vq; y += qq[u][j] * S[4 * u + j]; } \
;             y += dpp_f(y, 0xB1); y += dpp_f(y, 0x4E); ydst[(t_) * ystride] = y; } while (0)
; __device__ __forceinline__ void gla_job(const bf16_t* P, bf16_t* Y, int l, int b, int h, LAS float* lds, int wave_s) {
;     ...
;             GLA_LD(0, a0_, k0_, q0_, v0_);
;             for (int t = 0; t < TC; t += 2) {
;                 GLA_LD(t + 1, a1_, k1_, q1_, v1_);
;                 GLA_STEP(t, a0_, k0_, q0_, v0_);
;                 GLA_LD(t + 2 < TC ? t + 2 : t + 1, a0_, k0_, q0_, v0_);
;                 GLA_STEP(t + 1, a1_, k1_, q1_, v1_);
;             }
	v_mul_f32_e32 v26, v0, v26
	v_mul_f32_e32 v27, v1, v27
	v_mul_f32_e32 v28, v2, v28
	v_mul_f32_e32 v29, v3, v29
	v_mul_f32_e32 v30, v4, v30
	v_mul_f32_e32 v31, v5, v31
	v_mul_f32_e32 v32, v6, v32
	v_mul_f32_e32 v34, v7, v34
	v_add_f32_dpp v35, v35, v35 quad_perm:[2,3,0,1] row_mask:0xf bank_mask:0xf bound_ctrl:1
	ds_write_b32 v174, v35
	v_add_u32_e32 v174, v174, v161
	v_fmac_f32_e32 v26, v8, v33
	v_fmac_f32_e32 v27, v9, v33
	v_fmac_f32_e32 v28, v10, v33
	v_fmac_f32_e32 v29, v11, v33
	v_fmac_f32_e32 v30, v12, v33
	v_fmac_f32_e32 v31, v13, v33
	v_fmac_f32_e32 v32, v14, v33
	v_fmac_f32_e32 v34, v15, v33
	v_mul_f32_e32 v40, v16, v26
	v_mul_f32_e32 v41, v17, v27
	v_fmac_f32_e32 v40, v18, v28
	v_fmac_f32_e32 v41, v19, v29
	v_fmac_f32_e32 v40, v20, v30
	v_fmac_f32_e32 v41, v21, v31
	v_fmac_f32_e32 v40, v22, v32
	v_fmac_f32_e32 v41, v23, v34
	v_add_f32_e32 v35, v40, v41
	s_nop 1
	v_add_f32_dpp v35, v35, v35 quad_perm:[1,0,3,2] row_mask:0xf bank_mask:0xf bound_ctrl:1
	ds_read_b128 v[0:3], v24 offset:17024
	ds_read_b128 v[4:7], v24 offset:17040
	ds_read_b128 v[8:11], v24 offset:8832
	ds_read_b128 v[12:15], v24 offset:8848
	ds_read_b32 v33, v171 offset:25856
	ds_read_b128 v[16:19], v24 offset:640
	ds_read_b128 v[20:23], v24 offset:656
	s_waitcnt lgkmcnt(7)
	v_mul_f32_e32 v26, v176, v26
	v_mul_f32_e32 v27, v177, v27
	v_mul_f32_e32 v28, v178, v28
	v_mul_f32_e32 v29, v179, v29
	v_mul_f32_e32 v30, v180, v30
	v_mul_f32_e32 v31, v181, v31
	v_mul_f32_e32 v32, v182, v32
	v_mul_f32_e32 v34, v183, v34
	v_add_f32_dpp v35, v35, v35 quad_perm:[2,3,0,1] row_mask:0xf bank_mask:0xf bound_ctrl:1
	ds_write_b32 v174, v35
	v_add_u32_e32 v174, v174, v161
	v_fmac_f32_e32 v26, v184, v200
	v_fmac_f32_e32 v27, v185, v200
	v_fmac_f32_e32 v28, v186, v200
	v_fmac_f32_e32 v29, v187, v200
	v_fmac_f32_e32 v30, v188, v200
	v_fmac_f32_e32 v31, v189, v200
	v_fmac_f32_e32 v32, v190, v200
	v_fmac_f32_e32 v34, v191, v200
	v_mul_f32_e32 v40, v192, v26
	v_mul_f32_e32 v41, v193, v27
	v_fmac_f32_e32 v40, v194, v28
	v_fmac_f32_e32 v41, v195, v29
	v_fmac_f32_e32 v40, v196, v30
	v_fmac_f32_e32 v41, v197, v31
	v_fmac_f32_e32 v40, v198, v32
	v_fmac_f32_e32 v41, v199, v34
	v_add_f32_e32 v35, v40, v41
	s_nop 1
	v_add_f32_dpp v35, v35, v35 quad_perm:[1,0,3,2] row_mask:0xf bank_mask:0xf bound_ctrl:1
	ds_read_b128 v[176:179], v24 offset:17152
	ds_read_b128 v[180:183], v24 offset:17168
	ds_read_b128 v[184:187], v24 offset:8960
	ds_read_b128 v[188:191], v24 offset:8976
	ds_read_b32 v200, v171 offset:26112
	ds_read_b128 v[192:195], v24 offset:768
	ds_read_b128 v[196:199], v24 offset:784
	s_waitcnt lgkmcnt(7)
	v_mul_f32_e32 v26, v0, v26
	v_mul_f32_e32 v27, v1, v27
	v_mul_f32_e32 v28, v2, v28
	v_mul_f32_e32 v29, v3, v29
	v_mul_f32_e32 v30, v4, v30
	v_mul_f32_e32 v31, v5, v31
	v_mul_f32_e32 v32, v6, v32
	v_mul_f32_e32 v34, v7, v34
	v_add_f32_dpp v35, v35, v35 quad_perm:[2,3,0,1] row_mask:0xf bank_mask:0xf bound_ctrl:1
	ds_write_b32 v174, v35
	v_add_u32_e32 v174, v174, v161
	v_fmac_f32_e32 v26, v8, v33
	v_fmac_f32_e32 v27, v9, v33
	v_fmac_f32_e32 v28, v10, v33
	v_fmac_f32_e32 v29, v11, v33
	v_fmac_f32_e32 v30, v12, v33
	v_fmac_f32_e32 v31, v13, v33
	v_fmac_f32_e32 v32, v14, v33
	v_fmac_f32_e32 v34, v15, v33
	v_mul_f32_e32 v40, v16, v26
	v_mul_f32_e32 v41, v17, v27
	v_fmac_f32_e32 v40, v18, v28
	v_fmac_f32_e32 v41, v19, v29
	v_fmac_f32_e32 v40, v20, v30
	v_fmac_f32_e32 v41, v21, v31
	v_fmac_f32_e32 v40, v22, v32
	v_fmac_f32_e32 v41, v23, v34
	v_add_f32_e32 v35, v40, v41
	s_nop 1
	v_add_f32_dpp v35, v35, v35 quad_perm:[1,0,3,2] row_mask:0xf bank_mask:0xf bound_ctrl:1
	ds_read_b128 v[0:3], v24 offset:17280
	ds_read_b128 v[4:7], v24 offset:17296
	ds_read_b128 v[8:11], v24 offset:9088
	ds_read_b128 v[12:15], v24 offset:9104
	ds_read_b32 v33, v171 offset:26368
	ds_read_b128 v[16:19], v24 offset:896
	ds_read_b128 v[20:23], v24 offset:912
	s_waitcnt lgkmcnt(7)
	v_mul_f32_e32 v26, v176, v26
	v_mul_f32_e32 v27, v177, v27
	v_mul_f32_e32 v28, v178, v28
	v_mul_f32_e32 v29, v179, v29
	v_mul_f32_e32 v30, v180, v30
	v_mul_f32_e32 v31, v181, v31
	v_mul_f32_e32 v32, v182, v32
	v_mul_f32_e32 v34, v183, v34
	v_add_f32_dpp v35, v35, v35 quad_perm:[2,3,0,1] row_mask:0xf bank_mask:0xf bound_ctrl:1
	ds_write_b32 v174, v35
	v_add_u32_e32 v174, v174, v161
	v_fmac_f32_e32 v26, v184, v200
	v_fmac_f32_e32 v27, v185, v200
	v_fmac_f32_e32 v28, v186, v200
	v_fmac_f32_e32 v29, v187, v200
	v_fmac_f32_e32 v30, v188, v200
	v_fmac_f32_e32 v31, v189, v200
	v_fmac_f32_e32 v32, v190, v200
	v_fmac_f32_e32 v34, v191, v200
	v_mul_f32_e32 v40, v192, v26
	v_mul_f32_e32 v41, v193, v27
	v_fmac_f32_e32 v40, v194, v28
	v_fmac_f32_e32 v41, v195, v29
	v_fmac_f32_e32 v40, v196, v30
	v_fmac_f32_e32 v41, v197, v31
	v_fmac_f32_e32 v40, v198, v32
	v_fmac_f32_e32 v41, v199, v34
	v_add_f32_e32 v35, v40, v41
	s_nop 1
	v_add_f32_dpp v35, v35, v35 quad_perm:[1,0,3,2] row_mask:0xf bank_mask:0xf bound_ctrl:1
	ds_read_b128 v[176:179], v24 offset:17408
	ds_read_b128 v[180:183], v24 offset:17424
	ds_read_b128 v[184:187], v24 offset:9216
	ds_read_b128 v[188:191], v24 offset:9232
	ds_read_b32 v200, v171 offset:26624
	ds_read_b128 v[192:195], v24 offset:1024
	ds_read_b128 v[196:199], v24 offset:1040
	s_waitcnt lgkmcnt(7)
	v_mul_f32_e32 v26, v0, v26
	v_mul_f32_e32 v27, v1, v27
	v_mul_f32_e32 v28, v2, v28
	v_mul_f32_e32 v29, v3, v29
	v_mul_f32_e32 v30, v4, v30
	v_mul_f32_e32 v31, v5, v31
	v_mul_f32_e32 v32, v6, v32
	v_mul_f32_e32 v34, v7, v34
	v_add_f32_dpp v35, v35, v35 quad_perm:[2,3,0,1] row_mask:0xf bank_mask:0xf bound_ctrl:1
	ds_write_b32 v174, v35
	v_add_u32_e32 v174, v174, v161
	v_fmac_f32_e32 v26, v8, v33
	v_fmac_f32_e32 v27, v9, v33
	v_fmac_f32_e32 v28, v10, v33
	v_fmac_f32_e32 v29, v11, v33
	v_fmac_f32_e32 v30, v12, v33
	v_fmac_f32_e32 v31, v13, v33
	v_fmac_f32_e32 v32, v14, v33
	v_fmac_f32_e32 v34, v15, v33
	v_mul_f32_e32 v40, v16, v26
	v_mul_f32_e32 v41, v17, v27
	v_fmac_f32_e32 v40, v18, v28
	v_fmac_f32_e32 v41, v19, v29
	v_fmac_f32_e32 v40, v20, v30
	v_fmac_f32_e32 v41, v21, v31
	v_fmac_f32_e32 v40, v22, v32
	v_fmac_f32_e32 v41, v23, v34
	v_add_f32_e32 v35, v40, v41
	s_nop 1
	v_add_f32_dpp v35, v35, v35 quad_perm:[1,0,3,2] row_mask:0xf bank_mask:0xf bound_ctrl:1
	v_add_u32_e32 v24, 0x400, v24
	v_add_u32_e32 v171, 0x800, v171
	s_add_i32 s6, s6, 1
	s_cmp_lt_u32 s6, 7
	s_cbranch_scc1 .Lgla_rec_334
; #define GLA_LD(t_, aq, kq, qq, vq) do { const int tt_ = (t_); vq = Bs[6144 + tt_ * 64 + pp]; \
;             _Pragma("unroll") for (int u = 0; u < 2; ++u) { aq[u] = *(const LAS f32x4*)(Bs + 4096 + tt_ * 32 + k0 + 4 * u); kq[u] = *(const LAS f32x4*)(Bs + 2048 + tt_ * 32 + k0 + 4 * u); qq[u] = *(const LAS f32x4*)(Bs + tt_ * 32 + k0 + 4 * u); } } while (0)
; #define GLA_STEP(t_, aq, kq, qq, vq) do { float y = 0.f; \
;             _Pragma("unroll") for (int u = 0; u < 2; ++u) _Pragma("unroll") for (int j = 0; j < 4; ++j) { S[4 * u + j] = aq[u][j] * S[4 * u + j] + kq[u][j] * vq; y += qq[u][j] * S[4 * u + j]; } \
;             y += dpp_f(y, 0xB1); y += dpp_f(y, 0x4E); ydst[(t_) * ystride] = y; } while (0)
; __device__ __forceinline__ void gla_job(const bf16_t* P, bf16_t* Y, int l, int b, int h, LAS float* lds, int wave_s) {
;     ...
;             GLA_LD(0, a0_, k0_, q0_, v0_);
;             for (int t = 0; t < TC; t += 2) {
;                 GLA_LD(t + 1, a1_, k1_, q1_, v1_);
;                 GLA_STEP(t, a0_, k0_, q0_, v0_);
;                 GLA_LD(t + 2 < TC ? t + 2 : t + 1, a0_, k0_, q0_, v0_);
;                 GLA_STEP(t + 1, a1_, k1_, q1_, v1_);
;             }
	ds_read_b128 v[0:3], v24 offset:16512
	ds_read_b128 v[4:7], v24 offset:16528
	ds_read_b128 v[8:11], v24 offset:8320
	ds_read_b128 v[12:15], v24 offset:8336
	ds_read_b32 v33, v171 offset:24832
	ds_read_b128 v[16:19], v24 offset:128
	ds_read_b128 v[20:23], v24 offset:144
	s_waitcnt lgkmcnt(7)
	v_mul_f32_e32 v26, v176, v26
	v_mul_f32_e32 v27, v177, v27
	v_mul_f32_e32 v28, v178, v28
	v_mul_f32_e32 v29, v179, v29
	v_mul_f32_e32 v30, v180, v30
	v_mul_f32_e32 v31, v181, v31
	v_mul_f32_e32 v32, v182, v32
	v_mul_f32_e32 v34, v183, v34
	v_add_f32_dpp v35, v35, v35 quad_perm:[2,3,0,1] row_mask:0xf bank_mask:0xf bound_ctrl:1
	ds_write_b32 v174, v35
	v_add_u32_e32 v174, v174, v161
	v_fmac_f32_e32 v26, v184, v200
	v_fmac_f32_e32 v27, v185, v200
	v_fmac_f32_e32 v28, v186, v200
	v_fmac_f32_e32 v29, v187, v200
	v_fmac_f32_e32 v30, v188, v200
	v_fmac_f32_e32 v31, v189, v200
	v_fmac_f32_e32 v32, v190, v200
	v_fmac_f32_e32 v34, v191, v200
	v_mul_f32_e32 v40, v192, v26
	v_mul_f32_e32 v41, v193, v27
	v_fmac_f32_e32 v40, v194, v28
	v_fmac_f32_e32 v41, v195, v29
	v_fmac_f32_e32 v40, v196, v30
	v_fmac_f32_e32 v41, v197, v31
	v_fmac_f32_e32 v40, v198, v32
	v_fmac_f32_e32 v41, v199, v34
	v_add_f32_e32 v35, v40, v41
	s_nop 1
	v_add_f32_dpp v35, v35, v35 quad_perm:[1,0,3,2] row_mask:0xf bank_mask:0xf bound_ctrl:1
	ds_read_b128 v[176:179], v24 offset:16640
	ds_read_b128 v[180:183], v24 offset:16656
	ds_read_b128 v[184:187], v24 offset:8448
	ds_read_b128 v[188:191], v24 offset:8464
	ds_read_b32 v200, v171 offset:25088
	ds_read_b128 v[192:195], v24 offset:256
	ds_read_b128 v[196:199], v24 offset:272
	s_waitcnt lgkmcnt(7)
	v_mul_f32_e32 v26, v0, v26
	v_mul_f32_e32 v27, v1, v27
	v_mul_f32_e32 v28, v2, v28
	v_mul_f32_e32 v29, v3, v29
	v_mul_f32_e32 v30, v4, v30
	v_mul_f32_e32 v31, v5, v31
	v_mul_f32_e32 v32, v6, v32
	v_mul_f32_e32 v34, v7, v34
	v_add_f32_dpp v35, v35, v35 quad_perm:[2,3,0,1] row_mask:0xf bank_mask:0xf bound_ctrl:1
	ds_write_b32 v174, v35
	v_add_u32_e32 v174, v174, v161
	v_fmac_f32_e32 v26, v8, v33
	v_fmac_f32_e32 v27, v9, v33
	v_fmac_f32_e32 v28, v10, v33
	v_fmac_f32_e32 v29, v11, v33
	v_fmac_f32_e32 v30, v12, v33
	v_fmac_f32_e32 v31, v13, v33
	v_fmac_f32_e32 v32, v14, v33
	v_fmac_f32_e32 v34, v15, v33
	v_mul_f32_e32 v40, v16, v26
	v_mul_f32_e32 v41, v17, v27
	v_fmac_f32_e32 v40, v18, v28
	v_fmac_f32_e32 v41, v19, v29
	v_fmac_f32_e32 v40, v20, v30
	v_fmac_f32_e32 v41, v21, v31
	v_fmac_f32_e32 v40, v22, v32
	v_fmac_f32_e32 v41, v23, v34
	v_add_f32_e32 v35, v40, v41
	s_nop 1
	v_add_f32_dpp v35, v35, v35 quad_perm:[1,0,3,2] row_mask:0xf bank_mask:0xf bound_ctrl:1
	ds_read_b128 v[0:3], v24 offset:16768
	ds_read_b128 v[4:7], v24 offset:16784
	ds_read_b128 v[8:11], v24 offset:8576
	ds_read_b128 v[12:15], v24 offset:8592
	ds_read_b32 v33, v171 offset:25344
	ds_read_b128 v[16:19], v24 offset:384
	ds_read_b128 v[20:23], v24 offset:400
	s_waitcnt lgkmcnt(7)
	v_mul_f32_e32 v26, v176, v26
	v_mul_f32_e32 v27, v177, v27
	v_mul_f32_e32 v28, v178, v28
	v_mul_f32_e32 v29, v179, v29
	v_mul_f32_e32 v30, v180, v30
	v_mul_f32_e32 v31, v181, v31
	v_mul_f32_e32 v32, v182, v32
	v_mul_f32_e32 v34, v183, v34
	v_add_f32_dpp v35, v35, v35 quad_perm:[2,3,0,1] row_mask:0xf bank_mask:0xf bound_ctrl:1
	ds_write_b32 v174, v35
	v_add_u32_e32 v174, v174, v161
	v_fmac_f32_e32 v26, v184, v200
	v_fmac_f32_e32 v27, v185, v200
	v_fmac_f32_e32 v28, v186, v200
	v_fmac_f32_e32 v29, v187, v200
	v_fmac_f32_e32 v30, v188, v200
	v_fmac_f32_e32 v31, v189, v200
	v_fmac_f32_e32 v32, v190, v200
	v_fmac_f32_e32 v34, v191, v200
	v_mul_f32_e32 v40, v192, v26
	v_mul_f32_e32 v41, v193, v27
	v_fmac_f32_e32 v40, v194, v28
	v_fmac_f32_e32 v41, v195, v29
	v_fmac_f32_e32 v40, v196, v30
	v_fmac_f32_e32 v41, v197, v31
	v_fmac_f32_e32 v40, v198, v32
	v_fmac_f32_e32 v41, v199, v34
	v_add_f32_e32 v35, v40, v41
	s_nop 1
	v_add_f32_dpp v35, v35, v35 quad_perm:[1,0,3,2] row_mask:0xf bank_mask:0xf bound_ctrl:1
	ds_read_b128 v[176:179], v24 offset:16896
	ds_read_b128 v[180:183], v24 offset:16912
	ds_read_b128 v[184:187], v24 offset:8704
	ds_read_b128 v[188:191], v24 offset:8720
	ds_read_b32 v200, v171 offset:25600
	ds_read_b128 v[192:195], v24 offset:512
	ds_read_b128 v[196:199], v24 offset:528
	s_waitcnt lgkmcnt(7)
; #define GLA_LD(t_, aq, kq, qq, vq) do { const int tt_ = (t_); vq = Bs[6144 + tt_ * 64 + pp]; \
;             _Pragma("unroll") for (int u = 0; u < 2; ++u) { aq[u] = *(const LAS f32x4*)(Bs + 4096 + tt_ * 32 + k0 + 4 * u); kq[u] = *(const LAS f32x4*)(Bs + 2048 + tt_ * 32 + k0 + 4 * u); qq[u] = *(const LAS f32x4*)(Bs + tt_ * 32 + k0 + 4 * u); } } while (0)
; #define GLA_STEP(t_, aq, kq, qq, vq) do { float y = 0.f; \
;             _Pragma("unroll") for (int u = 0; u < 2; ++u) _Pragma("unroll") for (int j = 0; j < 4; ++j) { S[4 * u + j] = aq[u][j] * S[4 * u + j] + kq[u][j] * vq; y += qq[u][j] * S[4 * u + j]; } \
;             y += dpp_f(y, 0xB1); y += dpp_f(y, 0x4E); ydst[(t_) * ystride] = y; } while (0)
; __device__ __forceinline__ void gla_job(const bf16_t* P, bf16_t* Y, int l, int b, int h, LAS float* lds, int wave_s) {
;     ...
;             GLA_LD(0, a0_, k0_, q0_, v0_);
;             for (int t = 0; t < TC; t += 2) {
;                 GLA_LD(t + 1, a1_, k1_, q1_, v1_);
;                 GLA_STEP(t, a0_, k0_, q0_, v0_);
;                 GLA_LD(t + 2 < TC ? t + 2 : t + 1, a0_, k0_, q0_, v0_);
;                 GLA_STEP(t + 1, a1_, k1_, q1_, v1_);
;             }
	v_mul_f32_e32 v26, v0, v26
	v_mul_f32_e32 v27, v1, v27
	v_mul_f32_e32 v28, v2, v28
	v_mul_f32_e32 v29, v3, v29
	v_mul_f32_e32 v30, v4, v30
	v_mul_f32_e32 v31, v5, v31
	v_mul_f32_e32 v32, v6, v32
	v_mul_f32_e32 v34, v7, v34
	v_add_f32_dpp v35, v35, v35 quad_perm:[2,3,0,1] row_mask:0xf bank_mask:0xf bound_ctrl:1
	ds_write_b32 v174, v35
	v_add_u32_e32 v174, v174, v161
	v_fmac_f32_e32 v26, v8, v33
	v_fmac_f32_e32 v27, v9, v33
	v_fmac_f32_e32 v28, v10, v33
	v_fmac_f32_e32 v29, v11, v33
	v_fmac_f32_e32 v30, v12, v33
	v_fmac_f32_e32 v31, v13, v33
	v_fmac_f32_e32 v32, v14, v33
	v_fmac_f32_e32 v34, v15, v33
	v_mul_f32_e32 v40, v16, v26
	v_mul_f32_e32 v41, v17, v27
	v_fmac_f32_e32 v40, v18, v28
	v_fmac_f32_e32 v41, v19, v29
	v_fmac_f32_e32 v40, v20, v30
	v_fmac_f32_e32 v41, v21, v31
	v_fmac_f32_e32 v40, v22, v32
	v_fmac_f32_e32 v41, v23, v34
	v_add_f32_e32 v35, v40, v41
	s_nop 1
	v_add_f32_dpp v35, v35, v35 quad_perm:[1,0,3,2] row_mask:0xf bank_mask:0xf bound_ctrl:1
	ds_read_b128 v[0:3], v24 offset:17024
	ds_read_b128 v[4:7], v24 offset:17040
	ds_read_b128 v[8:11], v24 offset:8832
	ds_read_b128 v[12:15], v24 offset:8848
	ds_read_b32 v33, v171 offset:25856
	ds_read_b128 v[16:19], v24 offset:640
	ds_read_b128 v[20:23], v24 offset:656
	s_waitcnt lgkmcnt(7)
	v_mul_f32_e32 v26, v176, v26
	v_mul_f32_e32 v27, v177, v27
	v_mul_f32_e32 v28, v178, v28
	v_mul_f32_e32 v29, v179, v29
	v_mul_f32_e32 v30, v180, v30
	v_mul_f32_e32 v31, v181, v31
	v_mul_f32_e32 v32, v182, v32
	v_mul_f32_e32 v34, v183, v34
	v_add_f32_dpp v35, v35, v35 quad_perm:[2,3,0,1] row_mask:0xf bank_mask:0xf bound_ctrl:1
	ds_write_b32 v174, v35
	v_add_u32_e32 v174, v174, v161
	v_fmac_f32_e32 v26, v184, v200
	v_fmac_f32_e32 v27, v185, v200
	v_fmac_f32_e32 v28, v186, v200
	v_fmac_f32_e32 v29, v187, v200
	v_fmac_f32_e32 v30, v188, v200
	v_fmac_f32_e32 v31, v189, v200
	v_fmac_f32_e32 v32, v190, v200
	v_fmac_f32_e32 v34, v191, v200
	v_mul_f32_e32 v40, v192, v26
	v_mul_f32_e32 v41, v193, v27
	v_fmac_f32_e32 v40, v194, v28
	v_fmac_f32_e32 v41, v195, v29
	v_fmac_f32_e32 v40, v196, v30
	v_fmac_f32_e32 v41, v197, v31
	v_fmac_f32_e32 v40, v198, v32
	v_fmac_f32_e32 v41, v199, v34
	v_add_f32_e32 v35, v40, v41
	s_nop 1
	v_add_f32_dpp v35, v35, v35 quad_perm:[1,0,3,2] row_mask:0xf bank_mask:0xf bound_ctrl:1
	ds_read_b128 v[176:179], v24 offset:17152
	ds_read_b128 v[180:183], v24 offset:17168
	ds_read_b128 v[184:187], v24 offset:8960
	ds_read_b128 v[188:191], v24 offset:8976
	ds_read_b32 v200, v171 offset:26112
	ds_read_b128 v[192:195], v24 offset:768
	ds_read_b128 v[196:199], v24 offset:784
	s_waitcnt lgkmcnt(7)
	v_mul_f32_e32 v26, v0, v26
	v_mul_f32_e32 v27, v1, v27
	v_mul_f32_e32 v28, v2, v28
	v_mul_f32_e32 v29, v3, v29
	v_mul_f32_e32 v30, v4, v30
	v_mul_f32_e32 v31, v5, v31
	v_mul_f32_e32 v32, v6, v32
	v_mul_f32_e32 v34, v7, v34
	v_add_f32_dpp v35, v35, v35 quad_perm:[2,3,0,1] row_mask:0xf bank_mask:0xf bound_ctrl:1
	ds_write_b32 v174, v35
	v_add_u32_e32 v174, v174, v161
	v_fmac_f32_e32 v26, v8, v33
	v_fmac_f32_e32 v27, v9, v33
	v_fmac_f32_e32 v28, v10, v33
	v_fmac_f32_e32 v29, v11, v33
	v_fmac_f32_e32 v30, v12, v33
	v_fmac_f32_e32 v31, v13, v33
	v_fmac_f32_e32 v32, v14, v33
	v_fmac_f32_e32 v34, v15, v33
	v_mul_f32_e32 v40, v16, v26
	v_mul_f32_e32 v41, v17, v27
	v_fmac_f32_e32 v40, v18, v28
	v_fmac_f32_e32 v41, v19, v29
	v_fmac_f32_e32 v40, v20, v30
	v_fmac_f32_e32 v41, v21, v31
	v_fmac_f32_e32 v40, v22, v32
	v_fmac_f32_e32 v41, v23, v34
	v_add_f32_e32 v35, v40, v41
	s_nop 1
	v_add_f32_dpp v35, v35, v35 quad_perm:[1,0,3,2] row_mask:0xf bank_mask:0xf bound_ctrl:1
	s_waitcnt lgkmcnt(1)
	v_mul_f32_e32 v26, v176, v26
	v_mul_f32_e32 v27, v177, v27
	v_mul_f32_e32 v28, v178, v28
	v_mul_f32_e32 v29, v179, v29
	v_mul_f32_e32 v30, v180, v30
	v_mul_f32_e32 v31, v181, v31
	v_mul_f32_e32 v32, v182, v32
	v_mul_f32_e32 v34, v183, v34
	v_add_f32_dpp v35, v35, v35 quad_perm:[2,3,0,1] row_mask:0xf bank_mask:0xf bound_ctrl:1
	ds_write_b32 v174, v35
	v_add_u32_e32 v174, v174, v161
	v_fmac_f32_e32 v26, v184, v200
	v_fmac_f32_e32 v27, v185, v200
	v_fmac_f32_e32 v28, v186, v200
	v_fmac_f32_e32 v29, v187, v200
	v_fmac_f32_e32 v30, v188, v200
	v_fmac_f32_e32 v31, v189, v200
	v_fmac_f32_e32 v32, v190, v200
	v_fmac_f32_e32 v34, v191, v200
	v_mul_f32_e32 v40, v192, v26
	v_mul_f32_e32 v41, v193, v27
	v_fmac_f32_e32 v40, v194, v28
	v_fmac_f32_e32 v41, v195, v29
	v_fmac_f32_e32 v40, v196, v30
	v_fmac_f32_e32 v41, v197, v31
	v_fmac_f32_e32 v40, v198, v32
	v_fmac_f32_e32 v41, v199, v34
	v_add_f32_e32 v35, v40, v41
	s_nop 1
	v_add_f32_dpp v35, v35, v35 quad_perm:[1,0,3,2] row_mask:0xf bank_mask:0xf bound_ctrl:1
	s_nop 1
	v_add_f32_dpp v35, v35, v35 quad_perm:[2,3,0,1] row_mask:0xf bank_mask:0xf bound_ctrl:1
	ds_write_b32 v174, v35
	s_setprio 0
	s_branch .LBB0_324

; #define LAS __attribute__((address_space(3)))
; __device__ __forceinline__ void lru_job(const bf16_t* P, bf16_t* Y, int l, int b, int kb, LAS float* lds, int wave_s) {
;     ...
;         for (int tt = 0; tt < 8; ++tt) { const int t = tg * 8 + tt; f32x2_t dd = {ba, bx};
; #pragma unroll
;             for (int i4 = 0; i4 < 16; ++i4) { const f32x4 xv = *(const LAS f32x4*)(XC + t * 64 + 4 * i4);
; #pragma unroll
;                 for (int q = 0; q < 4; ++q) { const f32x2_t xb = {xv[q], xv[q]}; dd = __builtin_elementwise_fma(xb, wax[4 * i4 + q], dd); } }
.LBB0_955:
	ds_read_b128 v[40:43], v99
	ds_read_b128 v[56:59], v99 offset:4096
	ds_read_b128 v[44:47], v99 offset:16
	ds_read_b128 v[60:63], v99 offset:4112
	ds_read_b128 v[48:51], v99 offset:32
	ds_read_b128 v[64:67], v99 offset:4128
	ds_read_b128 v[52:55], v99 offset:48
	ds_read_b128 v[68:71], v99 offset:4144
	ds_read_b32 v88, v100
	ds_read_b32 v89, v100 offset:256
	ds_read_b32 v90, v100 offset:512
	ds_read_b32 v91, v100 offset:768
	ds_read_b32 v92, v100 offset:4096
	ds_read_b32 v93, v100 offset:4352
	ds_read_b32 v94, v100 offset:4608
	ds_read_b32 v95, v100 offset:4864
	v_mov_b32_e32 v72, v96
	v_mov_b32_e32 v73, v96
	v_mov_b32_e32 v74, v96
	v_mov_b32_e32 v75, v96
	v_mov_b32_e32 v76, v97
	v_mov_b32_e32 v77, v97
	v_mov_b32_e32 v78, v97
	v_mov_b32_e32 v79, v97
	v_mov_b32_e32 v80, v96
	v_mov_b32_e32 v81, v96
	v_mov_b32_e32 v82, v96
	v_mov_b32_e32 v83, v96
	v_mov_b32_e32 v84, v97
	v_mov_b32_e32 v85, v97
	v_mov_b32_e32 v86, v97
	v_mov_b32_e32 v87, v97
	s_waitcnt lgkmcnt(14)
	s_nop 1
	v_mfma_f32_16x16x4_f32 v[72:75], v40, v0, v[72:75]
	v_mfma_f32_16x16x4_f32 v[76:79], v40, v16, v[76:79]
	v_mfma_f32_16x16x4_f32 v[80:83], v56, v0, v[80:83]
	v_mfma_f32_16x16x4_f32 v[84:87], v56, v16, v[84:87]
	v_mfma_f32_16x16x4_f32 v[72:75], v41, v1, v[72:75]
	v_mfma_f32_16x16x4_f32 v[76:79], v41, v17, v[76:79]
	v_mfma_f32_16x16x4_f32 v[80:83], v57, v1, v[80:83]
	v_mfma_f32_16x16x4_f32 v[84:87], v57, v17, v[84:87]
	v_mfma_f32_16x16x4_f32 v[72:75], v42, v2, v[72:75]
	v_mfma_f32_16x16x4_f32 v[76:79], v42, v18, v[76:79]
	v_mfma_f32_16x16x4_f32 v[80:83], v58, v2, v[80:83]
	v_mfma_f32_16x16x4_f32 v[84:87], v58, v18, v[84:87]
	v_mfma_f32_16x16x4_f32 v[72:75], v43, v3, v[72:75]
	v_mfma_f32_16x16x4_f32 v[76:79], v43, v19, v[76:79]
	v_mfma_f32_16x16x4_f32 v[80:83], v59, v3, v[80:83]
	v_mfma_f32_16x16x4_f32 v[84:87], v59, v19, v[84:87]
	s_waitcnt lgkmcnt(12)
	v_mfma_f32_16x16x4_f32 v[72:75], v44, v4, v[72:75]
	v_mfma_f32_16x16x4_f32 v[76:79], v44, v20, v[76:79]
	v_mfma_f32_16x16x4_f32 v[80:83], v60, v4, v[80:83]
	v_mfma_f32_16x16x4_f32 v[84:87], v60, v20, v[84:87]
	v_mfma_f32_16x16x4_f32 v[72:75], v45, v5, v[72:75]
	v_mfma_f32_16x16x4_f32 v[76:79], v45, v21, v[76:79]
	v_mfma_f32_16x16x4_f32 v[80:83], v61, v5, v[80:83]
	v_mfma_f32_16x16x4_f32 v[84:87], v61, v21, v[84:87]
	v_mfma_f32_16x16x4_f32 v[72:75], v46, v6, v[72:75]
	v_mfma_f32_16x16x4_f32 v[76:79], v46, v22, v[76:79]
	v_mfma_f32_16x16x4_f32 v[80:83], v62, v6, v[80:83]
	v_mfma_f32_16x16x4_f32 v[84:87], v62, v22, v[84:87]
	v_mfma_f32_16x16x4_f32 v[72:75], v47, v7, v[72:75]
	v_mfma_f32_16x16x4_f32 v[76:79], v47, v23, v[76:79]
	v_mfma_f32_16x16x4_f32 v[80:83], v63, v7, v[80:83]
	v_mfma_f32_16x16x4_f32 v[84:87], v63, v23, v[84:87]
	s_waitcnt lgkmcnt(10)
	v_mfma_f32_16x16x4_f32 v[72:75], v48, v8, v[72:75]
	v_mfma_f32_16x16x4_f32 v[76:79], v48, v24, v[76:79]
	v_mfma_f32_16x16x4_f32 v[80:83], v64, v8, v[80:83]
	v_mfma_f32_16x16x4_f32 v[84:87], v64, v24, v[84:87]
	v_mfma_f32_16x16x4_f32 v[72:75], v49, v9, v[72:75]
	v_mfma_f32_16x16x4_f32 v[76:79], v49, v25, v[76:79]
	v_mfma_f32_16x16x4_f32 v[80:83], v65, v9, v[80:83]
	v_mfma_f32_16x16x4_f32 v[84:87], v65, v25, v[84:87]
	v_mfma_f32_16x16x4_f32 v[72:75], v50, v10, v[72:75]
	v_mfma_f32_16x16x4_f32 v[76:79], v50, v26, v[76:79]
	v_mfma_f32_16x16x4_f32 v[80:83], v66, v10, v[80:83]
	v_mfma_f32_16x16x4_f32 v[84:87], v66, v26, v[84:87]
	v_mfma_f32_16x16x4_f32 v[72:75], v51, v11, v[72:75]
	v_mfma_f32_16x16x4_f32 v[76:79], v51, v27, v[76:79]
	v_mfma_f32_16x16x4_f32 v[80:83], v67, v11, v[80:83]
	v_mfma_f32_16x16x4_f32 v[84:87], v67, v27, v[84:87]
	s_waitcnt lgkmcnt(8)
	v_mfma_f32_16x16x4_f32 v[72:75], v52, v12, v[72:75]
	v_mfma_f32_16x16x4_f32 v[76:79], v52, v28, v[76:79]
	v_mfma_f32_16x16x4_f32 v[80:83], v68, v12, v[80:83]
	v_mfma_f32_16x16x4_f32 v[84:87], v68, v28, v[84:87]
	v_mfma_f32_16x16x4_f32 v[72:75], v53, v13, v[72:75]
	v_mfma_f32_16x16x4_f32 v[76:79], v53, v29, v[76:79]
	v_mfma_f32_16x16x4_f32 v[80:83], v69, v13, v[80:83]
	v_mfma_f32_16x16x4_f32 v[84:87], v69, v29, v[84:87]
	v_mfma_f32_16x16x4_f32 v[72:75], v54, v14, v[72:75]
	v_mfma_f32_16x16x4_f32 v[76:79], v54, v30, v[76:79]
	v_mfma_f32_16x16x4_f32 v[80:83], v70, v14, v[80:83]
	v_mfma_f32_16x16x4_f32 v[84:87], v70, v30, v[84:87]
	v_mfma_f32_16x16x4_f32 v[72:75], v55, v15, v[72:75]
	v_mfma_f32_16x16x4_f32 v[76:79], v55, v31, v[76:79]
	v_mfma_f32_16x16x4_f32 v[80:83], v71, v15, v[80:83]
	v_mfma_f32_16x16x4_f32 v[84:87], v71, v31, v[84:87]
	s_waitcnt lgkmcnt(0)
; __device__ __forceinline__ float sigmoidf_(float x) { return __builtin_amdgcn_rcpf(1.f + __expf(-x)); }
; __device__ __forceinline__ void lru_job(const bf16_t* P, bf16_t* Y, int l, int b, int kb, LAS float* lds, int wave_s) {
;     ...
;             const float rg = sigmoidf_(dd.x), ig = sigmoidf_(dd.y);
;             const float la = -8.f * rg * spl;
;             const float av = __expf(la);
;             Aa[t * 64 + j] = av;
;             Uu[t * 64 + j] = sqrtf(fmaxf(1.f - av * av, 0.f)) * (ig * XC[t * 64 + j]); }
;         __syncthreads();
;         if (tid < 64) {
	s_nop 7
	s_nop 3
	v_mul_f32_e32 v101, 0xbfb8aa3b, v72
	v_mul_f32_e32 v104, 0xbfb8aa3b, v73
	v_exp_f32_e32 v101, v101
	v_exp_f32_e32 v104, v104
	v_mul_f32_e32 v102, 0xbfb8aa3b, v76
	v_mul_f32_e32 v105, 0xbfb8aa3b, v77
	v_exp_f32_e32 v102, v102
	v_exp_f32_e32 v105, v105
	v_add_f32_e32 v101, 1.0, v101
	v_add_f32_e32 v104, 1.0, v104
	v_rcp_f32_e32 v101, v101
	v_rcp_f32_e32 v104, v104
	v_add_f32_e32 v102, 1.0, v102
	v_add_f32_e32 v105, 1.0, v105
	v_rcp_f32_e32 v102, v102
	v_rcp_f32_e32 v105, v105
	v_mul_f32_e32 v101, 0xc1000000, v101
	v_mul_f32_e32 v104, 0xc1000000, v104
	v_mul_f32_e32 v101, v98, v101
	v_mul_f32_e32 v104, v98, v104
	v_mul_f32_e32 v101, 0x3fb8aa3b, v101
	v_mul_f32_e32 v104, 0x3fb8aa3b, v104
	v_exp_f32_e32 v101, v101
	v_exp_f32_e32 v104, v104
	v_mul_f32_e32 v102, v88, v102
	v_mul_f32_e32 v105, v89, v105
	v_fma_f32 v103, -v101, v101, 1.0
	v_fma_f32 v106, -v104, v104, 1.0
	v_max_f32_e32 v103, 0, v103
	v_max_f32_e32 v106, 0, v106
	v_sqrt_f32_e32 v103, v103
	v_sqrt_f32_e32 v106, v106
	s_nop 0
	s_nop 0
	v_mul_f32_e32 v102, v102, v103
	v_mul_f32_e32 v105, v105, v106
	ds_write2st64_b32 v100, v101, v102 offset0:64 offset1:128
	ds_write2st64_b32 v100, v104, v105 offset0:65 offset1:129
	v_mul_f32_e32 v101, 0xbfb8aa3b, v74
	v_mul_f32_e32 v104, 0xbfb8aa3b, v75
	v_exp_f32_e32 v101, v101
	v_exp_f32_e32 v104, v104
	v_mul_f32_e32 v102, 0xbfb8aa3b, v78
	v_mul_f32_e32 v105, 0xbfb8aa3b, v79
	v_exp_f32_e32 v102, v102
	v_exp_f32_e32 v105, v105
	v_add_f32_e32 v101, 1.0, v101
	v_add_f32_e32 v104, 1.0, v104
	v_rcp_f32_e32 v101, v101
	v_rcp_f32_e32 v104, v104
	v_add_f32_e32 v102, 1.0, v102
	v_add_f32_e32 v105, 1.0, v105
	v_rcp_f32_e32 v102, v102
	v_rcp_f32_e32 v105, v105
	v_mul_f32_e32 v101, 0xc1000000, v101
	v_mul_f32_e32 v104, 0xc1000000, v104
	v_mul_f32_e32 v101, v98, v101
	v_mul_f32_e32 v104, v98, v104
	v_mul_f32_e32 v101, 0x3fb8aa3b, v101
	v_mul_f32_e32 v104, 0x3fb8aa3b, v104
	v_exp_f32_e32 v101, v101
	v_exp_f32_e32 v104, v104
	v_mul_f32_e32 v102, v90, v102
	v_mul_f32_e32 v105, v91, v105
	v_fma_f32 v103, -v101, v101, 1.0
	v_fma_f32 v106, -v104, v104, 1.0
	v_max_f32_e32 v103, 0, v103
	v_max_f32_e32 v106, 0, v106
	v_sqrt_f32_e32 v103, v103
	v_sqrt_f32_e32 v106, v106
	s_nop 0
	s_nop 0
	v_mul_f32_e32 v102, v102, v103
	v_mul_f32_e32 v105, v105, v106
	ds_write2st64_b32 v100, v101, v102 offset0:66 offset1:130
	ds_write2st64_b32 v100, v104, v105 offset0:67 offset1:131
	v_mul_f32_e32 v101, 0xbfb8aa3b, v80
	v_mul_f32_e32 v104, 0xbfb8aa3b, v81
	v_exp_f32_e32 v101, v101
	v_exp_f32_e32 v104, v104
	v_mul_f32_e32 v102, 0xbfb8aa3b, v84
	v_mul_f32_e32 v105, 0xbfb8aa3b, v85
	v_exp_f32_e32 v102, v102
	v_exp_f32_e32 v105, v105
	v_add_f32_e32 v101, 1.0, v101
	v_add_f32_e32 v104, 1.0, v104
	v_rcp_f32_e32 v101, v101
	v_rcp_f32_e32 v104, v104
	v_add_f32_e32 v102, 1.0, v102
	v_add_f32_e32 v105, 1.0, v105
	v_rcp_f32_e32 v102, v102
	v_rcp_f32_e32 v105, v105
	v_mul_f32_e32 v101, 0xc1000000, v101
	v_mul_f32_e32 v104, 0xc1000000, v104
	v_mul_f32_e32 v101, v98, v101
	v_mul_f32_e32 v104, v98, v104
	v_mul_f32_e32 v101, 0x3fb8aa3b, v101
	v_mul_f32_e32 v104, 0x3fb8aa3b, v104
	v_exp_f32_e32 v101, v101
	v_exp_f32_e32 v104, v104
	v_mul_f32_e32 v102, v92, v102
	v_mul_f32_e32 v105, v93, v105
	v_fma_f32 v103, -v101, v101, 1.0
	v_fma_f32 v106, -v104, v104, 1.0
	v_max_f32_e32 v103, 0, v103
	v_max_f32_e32 v106, 0, v106
	v_sqrt_f32_e32 v103, v103
	v_sqrt_f32_e32 v106, v106
	s_nop 0
	s_nop 0
	v_mul_f32_e32 v102, v102, v103
	v_mul_f32_e32 v105, v105, v106
	ds_write2st64_b32 v100, v101, v102 offset0:80 offset1:144
	ds_write2st64_b32 v100, v104, v105 offset0:81 offset1:145
	v_mul_f32_e32 v101, 0xbfb8aa3b, v82
	v_mul_f32_e32 v104, 0xbfb8aa3b, v83
	v_exp_f32_e32 v101, v101
	v_exp_f32_e32 v104, v104
	v_mul_f32_e32 v102, 0xbfb8aa3b, v86
	v_mul_f32_e32 v105, 0xbfb8aa3b, v87
	v_exp_f32_e32 v102, v102
	v_exp_f32_e32 v105, v105
	v_add_f32_e32 v101, 1.0, v101
	v_add_f32_e32 v104, 1.0, v104
	v_rcp_f32_e32 v101, v101
	v_rcp_f32_e32 v104, v104
	v_add_f32_e32 v102, 1.0, v102
	v_add_f32_e32 v105, 1.0, v105
	v_rcp_f32_e32 v102, v102
	v_rcp_f32_e32 v105, v105
	v_mul_f32_e32 v101, 0xc1000000, v101
	v_mul_f32_e32 v104, 0xc1000000, v104
	v_mul_f32_e32 v101, v98, v101
	v_mul_f32_e32 v104, v98, v104
	v_mul_f32_e32 v101, 0x3fb8aa3b, v101
	v_mul_f32_e32 v104, 0x3fb8aa3b, v104
	v_exp_f32_e32 v101, v101
	v_exp_f32_e32 v104, v104
	v_mul_f32_e32 v102, v94, v102
	v_mul_f32_e32 v105, v95, v105
	v_fma_f32 v103, -v101, v101, 1.0
	v_fma_f32 v106, -v104, v104, 1.0
	v_max_f32_e32 v103, 0, v103
	v_max_f32_e32 v106, 0, v106
	v_sqrt_f32_e32 v103, v103
	v_sqrt_f32_e32 v106, v106
	s_nop 0
	s_nop 0
	v_mul_f32_e32 v102, v102, v103
	v_mul_f32_e32 v105, v105, v106
	ds_write2st64_b32 v100, v101, v102 offset0:82 offset1:146
	ds_write2st64_b32 v100, v104, v105 offset0:83 offset1:147
	s_waitcnt lgkmcnt(0)
	s_barrier
	s_and_saveexec_b64 s[4:5], vcc
	s_cbranch_execz .LBB0_952
; __device__ __forceinline__ void lru_job(const bf16_t* P, bf16_t* Y, int l, int b, int kb, LAS float* lds, int wave_s) {
;     ...
;         if (tid < 64) {
;             for (int tb = 0; tb < TC; tb += 8) { float av[8], uv[8];
; #pragma unroll
;                 for (int k = 0; k < 8; ++k) { av[k] = Aa[(tb + k) * 64 + j]; uv[k] = Uu[(tb + k) * 64 + j]; }
; #pragma unroll
;                 for (int k = 0; k < 8; ++k) { hs = av[k] * hs + uv[k]; Hh[(tb + k) * 64 + j] = hs; } }
;         }
	ds_read2st64_b32 v[216:217], v176 offset0:64 offset1:65
	ds_read2st64_b32 v[218:219], v176 offset0:66 offset1:67
	ds_read2st64_b32 v[220:221], v176 offset0:68 offset1:69
	ds_read2st64_b32 v[222:223], v176 offset0:70 offset1:71
	ds_read2st64_b32 v[224:225], v176 offset0:128 offset1:129
	ds_read2st64_b32 v[226:227], v176 offset0:130 offset1:131
	ds_read2st64_b32 v[228:229], v176 offset0:132 offset1:133
	ds_read2st64_b32 v[230:231], v176 offset0:134 offset1:135
	ds_read2st64_b32 v[234:235], v176 offset0:72 offset1:73
	ds_read2st64_b32 v[236:237], v176 offset0:74 offset1:75
	ds_read2st64_b32 v[238:239], v176 offset0:76 offset1:77
	ds_read2st64_b32 v[240:241], v176 offset0:78 offset1:79
	ds_read2st64_b32 v[242:243], v176 offset0:136 offset1:137
	ds_read2st64_b32 v[244:245], v176 offset0:138 offset1:139
	ds_read2st64_b32 v[246:247], v176 offset0:140 offset1:141
	ds_read2st64_b32 v[248:249], v176 offset0:142 offset1:143
	s_waitcnt lgkmcnt(8)
	v_fmac_f32_e32 v224, v135, v216
	v_fmac_f32_e32 v225, v224, v217
	v_fmac_f32_e32 v226, v225, v218
	v_fmac_f32_e32 v227, v226, v219
	v_fmac_f32_e32 v228, v227, v220
	v_fmac_f32_e32 v229, v228, v221
	v_fmac_f32_e32 v230, v229, v222
	v_fmac_f32_e32 v231, v230, v223
	ds_write2st64_b32 v176, v224, v225 offset0:192 offset1:193
	ds_write2st64_b32 v176, v226, v227 offset0:194 offset1:195
	ds_write2st64_b32 v176, v228, v229 offset0:196 offset1:197
	ds_write2st64_b32 v176, v230, v231 offset0:198 offset1:199
	ds_read2st64_b32 v[216:217], v176 offset0:80 offset1:81
	ds_read2st64_b32 v[218:219], v176 offset0:82 offset1:83
	ds_read2st64_b32 v[220:221], v176 offset0:84 offset1:85
	ds_read2st64_b32 v[222:223], v176 offset0:86 offset1:87
	ds_read2st64_b32 v[224:225], v176 offset0:144 offset1:145
	ds_read2st64_b32 v[226:227], v176 offset0:146 offset1:147
	ds_read2st64_b32 v[228:229], v176 offset0:148 offset1:149
	ds_read2st64_b32 v[230:231], v176 offset0:150 offset1:151
	s_waitcnt lgkmcnt(12)
	v_fmac_f32_e32 v242, v231, v234
	v_fmac_f32_e32 v243, v242, v235
	v_fmac_f32_e32 v244, v243, v236
	v_fmac_f32_e32 v245, v244, v237
	v_fmac_f32_e32 v246, v245, v238
	v_fmac_f32_e32 v247, v246, v239
	v_fmac_f32_e32 v248, v247, v240
	v_fmac_f32_e32 v249, v248, v241
	ds_write2st64_b32 v176, v242, v243 offset0:200 offset1:201
	ds_write2st64_b32 v176, v244, v245 offset0:202 offset1:203
	ds_write2st64_b32 v176, v246, v247 offset0:204 offset1:205
	ds_write2st64_b32 v176, v248, v249 offset0:206 offset1:207
	ds_read2st64_b32 v[234:235], v176 offset0:88 offset1:89
	ds_read2st64_b32 v[236:237], v176 offset0:90 offset1:91
	ds_read2st64_b32 v[238:239], v176 offset0:92 offset1:93
	ds_read2st64_b32 v[240:241], v176 offset0:94 offset1:95
	ds_read2st64_b32 v[242:243], v176 offset0:152 offset1:153
	ds_read2st64_b32 v[244:245], v176 offset0:154 offset1:155
	ds_read2st64_b32 v[246:247], v176 offset0:156 offset1:157
	ds_read2st64_b32 v[248:249], v176 offset0:158 offset1:159
	s_waitcnt lgkmcnt(12)
	v_fmac_f32_e32 v224, v249, v216
	v_fmac_f32_e32 v225, v224, v217
	v_fmac_f32_e32 v226, v225, v218
	v_fmac_f32_e32 v227, v226, v219
	v_fmac_f32_e32 v228, v227, v220
	v_fmac_f32_e32 v229, v228, v221
	v_fmac_f32_e32 v230, v229, v222
	v_fmac_f32_e32 v231, v230, v223
	ds_write2st64_b32 v176, v224, v225 offset0:208 offset1:209
	ds_write2st64_b32 v176, v226, v227 offset0:210 offset1:211
	ds_write2st64_b32 v176, v228, v229 offset0:212 offset1:213
	ds_write2st64_b32 v176, v230, v231 offset0:214 offset1:215
	ds_read2st64_b32 v[216:217], v176 offset0:96 offset1:97
	ds_read2st64_b32 v[218:219], v176 offset0:98 offset1:99
	ds_read2st64_b32 v[220:221], v176 offset0:100 offset1:101
	ds_read2st64_b32 v[222:223], v176 offset0:102 offset1:103
	ds_read2st64_b32 v[224:225], v176 offset0:160 offset1:161
	ds_read2st64_b32 v[226:227], v176 offset0:162 offset1:163
	ds_read2st64_b32 v[228:229], v176 offset0:164 offset1:165
	ds_read2st64_b32 v[230:231], v176 offset0:166 offset1:167
	s_waitcnt lgkmcnt(12)
; __device__ __forceinline__ void lru_job(const bf16_t* P, bf16_t* Y, int l, int b, int kb, LAS float* lds, int wave_s) {
;     ...
;         if (tid < 64) {
;             for (int tb = 0; tb < TC; tb += 8) { float av[8], uv[8];
; #pragma unroll
;                 for (int k = 0; k < 8; ++k) { av[k] = Aa[(tb + k) * 64 + j]; uv[k] = Uu[(tb + k) * 64 + j]; }
; #pragma unroll
;                 for (int k = 0; k < 8; ++k) { hs = av[k] * hs + uv[k]; Hh[(tb + k) * 64 + j] = hs; } }
;         }
	v_fmac_f32_e32 v242, v231, v234
	v_fmac_f32_e32 v243, v242, v235
	v_fmac_f32_e32 v244, v243, v236
	v_fmac_f32_e32 v245, v244, v237
	v_fmac_f32_e32 v246, v245, v238
	v_fmac_f32_e32 v247, v246, v239
	v_fmac_f32_e32 v248, v247, v240
	v_fmac_f32_e32 v249, v248, v241
	ds_write2st64_b32 v176, v242, v243 offset0:216 offset1:217
	ds_write2st64_b32 v176, v244, v245 offset0:218 offset1:219
	ds_write2st64_b32 v176, v246, v247 offset0:220 offset1:221
	ds_write2st64_b32 v176, v248, v249 offset0:222 offset1:223
	ds_read2st64_b32 v[234:235], v176 offset0:104 offset1:105
	ds_read2st64_b32 v[236:237], v176 offset0:106 offset1:107
	ds_read2st64_b32 v[238:239], v176 offset0:108 offset1:109
	ds_read2st64_b32 v[240:241], v176 offset0:110 offset1:111
	ds_read2st64_b32 v[242:243], v176 offset0:168 offset1:169
	ds_read2st64_b32 v[244:245], v176 offset0:170 offset1:171
	ds_read2st64_b32 v[246:247], v176 offset0:172 offset1:173
	ds_read2st64_b32 v[248:249], v176 offset0:174 offset1:175
	s_waitcnt lgkmcnt(12)
	v_fmac_f32_e32 v224, v249, v216
	v_fmac_f32_e32 v225, v224, v217
	v_fmac_f32_e32 v226, v225, v218
	v_fmac_f32_e32 v227, v226, v219
	v_fmac_f32_e32 v228, v227, v220
	v_fmac_f32_e32 v229, v228, v221
	v_fmac_f32_e32 v230, v229, v222
	v_fmac_f32_e32 v231, v230, v223
	ds_write2st64_b32 v176, v224, v225 offset0:224 offset1:225
	ds_write2st64_b32 v176, v226, v227 offset0:226 offset1:227
	ds_write2st64_b32 v176, v228, v229 offset0:228 offset1:229
	ds_write2st64_b32 v176, v230, v231 offset0:230 offset1:231
	ds_read2st64_b32 v[216:217], v176 offset0:112 offset1:113
	ds_read2st64_b32 v[218:219], v176 offset0:114 offset1:115
	ds_read2st64_b32 v[220:221], v176 offset0:116 offset1:117
	ds_read2st64_b32 v[222:223], v176 offset0:118 offset1:119
	ds_read2st64_b32 v[224:225], v176 offset0:176 offset1:177
	ds_read2st64_b32 v[226:227], v176 offset0:178 offset1:179
	ds_read2st64_b32 v[228:229], v176 offset0:180 offset1:181
	ds_read2st64_b32 v[230:231], v176 offset0:182 offset1:183
	s_waitcnt lgkmcnt(12)
	v_fmac_f32_e32 v242, v231, v234
	v_fmac_f32_e32 v243, v242, v235
	v_fmac_f32_e32 v244, v243, v236
	v_fmac_f32_e32 v245, v244, v237
	v_fmac_f32_e32 v246, v245, v238
	v_fmac_f32_e32 v247, v246, v239
	v_fmac_f32_e32 v248, v247, v240
	v_fmac_f32_e32 v249, v248, v241
	ds_write2st64_b32 v176, v242, v243 offset0:232 offset1:233
	ds_write2st64_b32 v176, v244, v245 offset0:234 offset1:235
	ds_write2st64_b32 v176, v246, v247 offset0:236 offset1:237
	ds_write2st64_b32 v176, v248, v249 offset0:238 offset1:239
	ds_read2st64_b32 v[234:235], v176 offset0:120 offset1:121
	ds_read2st64_b32 v[236:237], v176 offset0:122 offset1:123
	ds_read2st64_b32 v[238:239], v176 offset0:124 offset1:125
	ds_read2st64_b32 v[240:241], v176 offset0:126 offset1:127
	ds_read2st64_b32 v[242:243], v176 offset0:184 offset1:185
	ds_read2st64_b32 v[244:245], v176 offset0:186 offset1:187
	ds_read2st64_b32 v[246:247], v176 offset0:188 offset1:189
	ds_read2st64_b32 v[248:249], v176 offset0:190 offset1:191
	s_waitcnt lgkmcnt(12)
	v_fmac_f32_e32 v224, v249, v216
	v_fmac_f32_e32 v225, v224, v217
	v_fmac_f32_e32 v226, v225, v218
	v_fmac_f32_e32 v227, v226, v219
	v_fmac_f32_e32 v228, v227, v220
	v_fmac_f32_e32 v229, v228, v221
	v_fmac_f32_e32 v230, v229, v222
	v_fmac_f32_e32 v231, v230, v223
	ds_write2st64_b32 v176, v224, v225 offset0:240 offset1:241
	ds_write2st64_b32 v176, v226, v227 offset0:242 offset1:243
	ds_write2st64_b32 v176, v228, v229 offset0:244 offset1:245
	ds_write2st64_b32 v176, v230, v231 offset0:246 offset1:247
	s_waitcnt lgkmcnt(4)
	v_fmac_f32_e32 v242, v231, v234
	v_fmac_f32_e32 v243, v242, v235
	v_fmac_f32_e32 v244, v243, v236
	v_fmac_f32_e32 v245, v244, v237
	v_fmac_f32_e32 v246, v245, v238
	v_fmac_f32_e32 v247, v246, v239
	v_fmac_f32_e32 v248, v247, v240
	v_fmac_f32_e32 v249, v248, v241
	ds_write2st64_b32 v176, v242, v243 offset0:248 offset1:249
	ds_write2st64_b32 v176, v244, v245 offset0:250 offset1:251
	ds_write2st64_b32 v176, v246, v247 offset0:252 offset1:253
	ds_write2st64_b32 v176, v248, v249 offset0:254 offset1:255
	v_mov_b32_e32 v135, v249
	s_branch .LBB0_952

; #define LAS __attribute__((address_space(3)))
; #define GLA_LD(t_, aq, kq, qq, vq) do { const int tt_ = (t_); vq = Bs[6144 + tt_ * 64 + pp]; \
;             _Pragma("unroll") for (int u = 0; u < 2; ++u) { aq[u] = *(const LAS f32x4*)(Bs + 4096 + tt_ * 32 + k0 + 4 * u); kq[u] = *(const LAS f32x4*)(Bs + 2048 + tt_ * 32 + k0 + 4 * u); qq[u] = *(const LAS f32x4*)(Bs + tt_ * 32 + k0 + 4 * u); } } while (0)
; #define GLA_STEP(t_, aq, kq, qq, vq) do { float y = 0.f; \
;             _Pragma("unroll") for (int u = 0; u < 2; ++u) _Pragma("unroll") for (int j = 0; j < 4; ++j) { S[4 * u + j] = aq[u][j] * S[4 * u + j] + kq[u][j] * vq; y += qq[u][j] * S[4 * u + j]; } \
;             y += dpp_f(y, 0xB1); y += dpp_f(y, 0x4E); ydst[(t_) * ystride] = y; } while (0)
; __device__ __forceinline__ void gla_job(const bf16_t* P, bf16_t* Y, int l, int b, int h, LAS float* lds, int wave_s) {
;     ...
;         if (wave_s < 4) {
;             LAS float* ydst = (lane & 3) == 0 ? (Yl + (c & 1) * 4096 + pp) : (lds + (LDS_XB + 256) / 4 + lane); const int ystride = (lane & 3) == 0 ? 64 : 0;
;             f32x4 a0_[2], k0_[2], q0_[2], a1_[2], k1_[2], q1_[2]; float v0_, v1_;
;     ...
;             GLA_LD(0, a0_, k0_, q0_, v0_);
;             for (int t = 0; t < TC; t += 2) {
;                 GLA_LD(t + 1, a1_, k1_, q1_, v1_);
;                 GLA_STEP(t, a0_, k0_, q0_, v0_);
;                 GLA_LD(t + 2 < TC ? t + 2 : t + 1, a0_, k0_, q0_, v0_);
;                 GLA_STEP(t + 1, a1_, k1_, q1_, v1_);
;             }
.LBB0_1045:
	s_andn2_b64 vcc, exec, s[6:7]
	s_cbranch_vccnz .LBB0_1036
	s_waitcnt vmcnt(15)
	v_cndmask_b32_e64 v0, 0, 1, s[8:9]
	s_mov_b32 s6, 0xa000
	v_mul_lo_u32 v0, v0, s6
	v_lshl_add_u32 v174, v132, 2, s14
	v_add_u32_e32 v24, v164, v0
	v_add_u32_e32 v172, v165, v0
	v_lshl_add_u32 v35, s15, 14, v133
	v_lshl_add_u32 v173, v131, 2, s14
	v_cndmask_b32_e64 v175, v157, v35, s[4:5]
	v_mov_b32_e32 v24, v174
	v_mov_b32_e32 v172, v173
	s_setprio 3
	ds_read_b128 v[0:3], v24 offset:16384
	ds_read_b128 v[4:7], v24 offset:16400
	ds_read_b128 v[8:11], v24 offset:8192
	ds_read_b128 v[12:15], v24 offset:8208
	ds_read_b32 v33, v172 offset:24576
	ds_read_b128 v[16:19], v24
	ds_read_b128 v[20:23], v24 offset:16
	ds_read_b128 v[176:179], v24 offset:16512
	ds_read_b128 v[180:183], v24 offset:16528
	ds_read_b128 v[184:187], v24 offset:8320
	ds_read_b128 v[188:191], v24 offset:8336
	ds_read_b32 v200, v172 offset:24832
	ds_read_b128 v[192:195], v24 offset:128
	ds_read_b128 v[196:199], v24 offset:144
	s_waitcnt lgkmcnt(7)
	v_mul_f32_e32 v26, v0, v26
	v_mul_f32_e32 v27, v1, v27
	v_mul_f32_e32 v28, v2, v28
	v_mul_f32_e32 v29, v3, v29
	v_mul_f32_e32 v30, v4, v30
	v_mul_f32_e32 v31, v5, v31
	v_mul_f32_e32 v32, v6, v32
	v_mul_f32_e32 v34, v7, v34
	v_fmac_f32_e32 v26, v8, v33
	v_fmac_f32_e32 v27, v9, v33
	v_fmac_f32_e32 v28, v10, v33
	v_fmac_f32_e32 v29, v11, v33
	v_fmac_f32_e32 v30, v12, v33
	v_fmac_f32_e32 v31, v13, v33
	v_fmac_f32_e32 v32, v14, v33
	v_fmac_f32_e32 v34, v15, v33
	v_mul_f32_e32 v40, v16, v26
	v_mul_f32_e32 v41, v17, v27
	v_fmac_f32_e32 v40, v18, v28
	v_fmac_f32_e32 v41, v19, v29
	v_fmac_f32_e32 v40, v20, v30
	v_fmac_f32_e32 v41, v21, v31
	v_fmac_f32_e32 v40, v22, v32
	v_fmac_f32_e32 v41, v23, v34
	v_add_f32_e32 v35, v40, v41
	s_nop 1
	v_add_f32_dpp v35, v35, v35 quad_perm:[1,0,3,2] row_mask:0xf bank_mask:0xf bound_ctrl:1
	v_add_u32_e32 v24, 0x80, v24
	v_add_u32_e32 v172, 0x100, v172
	s_mov_b32 s6, 0
.Lgla_rec_1047:
	ds_read_b128 v[0:3], v24 offset:16512
	ds_read_b128 v[4:7], v24 offset:16528
	ds_read_b128 v[8:11], v24 offset:8320
	ds_read_b128 v[12:15], v24 offset:8336
	ds_read_b32 v33, v172 offset:24832
	ds_read_b128 v[16:19], v24 offset:128
	ds_read_b128 v[20:23], v24 offset:144
	s_waitcnt lgkmcnt(7)
	v_mul_f32_e32 v26, v176, v26
	v_mul_f32_e32 v27, v177, v27
	v_mul_f32_e32 v28, v178, v28
	v_mul_f32_e32 v29, v179, v29
	v_mul_f32_e32 v30, v180, v30
	v_mul_f32_e32 v31, v181, v31
	v_mul_f32_e32 v32, v182, v32
	v_mul_f32_e32 v34, v183, v34
	v_add_f32_dpp v35, v35, v35 quad_perm:[2,3,0,1] row_mask:0xf bank_mask:0xf bound_ctrl:1
	ds_write_b32 v175, v35
	v_add_u32_e32 v175, v175, v162
	v_fmac_f32_e32 v26, v184, v200
	v_fmac_f32_e32 v27, v185, v200
	v_fmac_f32_e32 v28, v186, v200
	v_fmac_f32_e32 v29, v187, v200
	v_fmac_f32_e32 v30, v188, v200
	v_fmac_f32_e32 v31, v189, v200
	v_fmac_f32_e32 v32, v190, v200
	v_fmac_f32_e32 v34, v191, v200
	v_mul_f32_e32 v40, v192, v26
	v_mul_f32_e32 v41, v193, v27
	v_fmac_f32_e32 v40, v194, v28
	v_fmac_f32_e32 v41, v195, v29
	v_fmac_f32_e32 v40, v196, v30
	v_fmac_f32_e32 v41, v197, v31
	v_fmac_f32_e32 v40, v198, v32
	v_fmac_f32_e32 v41, v199, v34
	v_add_f32_e32 v35, v40, v41
	s_nop 1
	v_add_f32_dpp v35, v35, v35 quad_perm:[1,0,3,2] row_mask:0xf bank_mask:0xf bound_ctrl:1
	ds_read_b128 v[176:179], v24 offset:16640
	ds_read_b128 v[180:183], v24 offset:16656
	ds_read_b128 v[184:187], v24 offset:8448
	ds_read_b128 v[188:191], v24 offset:8464
	ds_read_b32 v200, v172 offset:25088
	ds_read_b128 v[192:195], v24 offset:256
	ds_read_b128 v[196:199], v24 offset:272
	s_waitcnt lgkmcnt(7)
	v_mul_f32_e32 v26, v0, v26
	v_mul_f32_e32 v27, v1, v27
	v_mul_f32_e32 v28, v2, v28
	v_mul_f32_e32 v29, v3, v29
	v_mul_f32_e32 v30, v4, v30
	v_mul_f32_e32 v31, v5, v31
	v_mul_f32_e32 v32, v6, v32
	v_mul_f32_e32 v34, v7, v34
	v_add_f32_dpp v35, v35, v35 quad_perm:[2,3,0,1] row_mask:0xf bank_mask:0xf bound_ctrl:1
	ds_write_b32 v175, v35
	v_add_u32_e32 v175, v175, v162
	v_fmac_f32_e32 v26, v8, v33
	v_fmac_f32_e32 v27, v9, v33
	v_fmac_f32_e32 v28, v10, v33
	v_fmac_f32_e32 v29, v11, v33
	v_fmac_f32_e32 v30, v12, v33
	v_fmac_f32_e32 v31, v13, v33
	v_fmac_f32_e32 v32, v14, v33
	v_fmac_f32_e32 v34, v15, v33
	v_mul_f32_e32 v40, v16, v26
	v_mul_f32_e32 v41, v17, v27
	v_fmac_f32_e32 v40, v18, v28
	v_fmac_f32_e32 v41, v19, v29
	v_fmac_f32_e32 v40, v20, v30
	v_fmac_f32_e32 v41, v21, v31
	v_fmac_f32_e32 v40, v22, v32
	v_fmac_f32_e32 v41, v23, v34
	v_add_f32_e32 v35, v40, v41
	s_nop 1
	v_add_f32_dpp v35, v35, v35 quad_perm:[1,0,3,2] row_mask:0xf bank_mask:0xf bound_ctrl:1
	ds_read_b128 v[0:3], v24 offset:16768
	ds_read_b128 v[4:7], v24 offset:16784
	ds_read_b128 v[8:11], v24 offset:8576
	ds_read_b128 v[12:15], v24 offset:8592
	ds_read_b32 v33, v172 offset:25344
	ds_read_b128 v[16:19], v24 offset:384
	ds_read_b128 v[20:23], v24 offset:400
	s_waitcnt lgkmcnt(7)
	v_mul_f32_e32 v26, v176, v26
	v_mul_f32_e32 v27, v177, v27
	v_mul_f32_e32 v28, v178, v28
	v_mul_f32_e32 v29, v179, v29
	v_mul_f32_e32 v30, v180, v30
	v_mul_f32_e32 v31, v181, v31
	v_mul_f32_e32 v32, v182, v32
	v_mul_f32_e32 v34, v183, v34
	v_add_f32_dpp v35, v35, v35 quad_perm:[2,3,0,1] row_mask:0xf bank_mask:0xf bound_ctrl:1
	ds_write_b32 v175, v35
	v_add_u32_e32 v175, v175, v162
	v_fmac_f32_e32 v26, v184, v200
	v_fmac_f32_e32 v27, v185, v200
	v_fmac_f32_e32 v28, v186, v200
	v_fmac_f32_e32 v29, v187, v200
	v_fmac_f32_e32 v30, v188, v200
	v_fmac_f32_e32 v31, v189, v200
	v_fmac_f32_e32 v32, v190, v200
	v_fmac_f32_e32 v34, v191, v200
	v_mul_f32_e32 v40, v192, v26
	v_mul_f32_e32 v41, v193, v27
	v_fmac_f32_e32 v40, v194, v28
	v_fmac_f32_e32 v41, v195, v29
	v_fmac_f32_e32 v40, v196, v30
	v_fmac_f32_e32 v41, v197, v31
	v_fmac_f32_e32 v40, v198, v32
	v_fmac_f32_e32 v41, v199, v34
	v_add_f32_e32 v35, v40, v41
	s_nop 1
	v_add_f32_dpp v35, v35, v35 quad_perm:[1,0,3,2] row_mask:0xf bank_mask:0xf bound_ctrl:1
	ds_read_b128 v[176:179], v24 offset:16896
	ds_read_b128 v[180:183], v24 offset:16912
	ds_read_b128 v[184:187], v24 offset:8704
	ds_read_b128 v[188:191], v24 offset:8720
	ds_read_b32 v200, v172 offset:25600
	ds_read_b128 v[192:195], v24 offset:512
	ds_read_b128 v[196:199], v24 offset:528
	s_waitcnt lgkmcnt(7)
; #define GLA_LD(t_, aq, kq, qq, vq) do { const int tt_ = (t_); vq = Bs[6144 + tt_ * 64 + pp]; \
;             _Pragma("unroll") for (int u = 0; u < 2; ++u) { aq[u] = *(const LAS f32x4*)(Bs + 4096 + tt_ * 32 + k0 + 4 * u); kq[u] = *(const LAS f32x4*)(Bs + 2048 + tt_ * 32 + k0 + 4 * u); qq[u] = *(const LAS f32x4*)(Bs + tt_ * 32 + k0 + 4 * u); } } while (0)
; #define GLA_STEP(t_, aq, kq, qq, vq) do { float y = 0.f; \
;             _Pragma("unroll") for (int u = 0; u < 2; ++u) _Pragma("unroll") for (int j = 0; j < 4; ++j) { S[4 * u + j] = aq[u][j] * S[4 * u + j] + kq[u][j] * vq; y += qq[u][j] * S[4 * u + j]; } \
;             y += dpp_f(y, 0xB1); y += dpp_f(y, 0x4E); ydst[(t_) * ystride] = y; } while (0)
; __device__ __forceinline__ void gla_job(const bf16_t* P, bf16_t* Y, int l, int b, int h, LAS float* lds, int wave_s) {
;     ...
;             GLA_LD(0, a0_, k0_, q0_, v0_);
;             for (int t = 0; t < TC; t += 2) {
;                 GLA_LD(t + 1, a1_, k1_, q1_, v1_);
;                 GLA_STEP(t, a0_, k0_, q0_, v0_);
;                 GLA_LD(t + 2 < TC ? t + 2 : t + 1, a0_, k0_, q0_, v0_);
;                 GLA_STEP(t + 1, a1_, k1_, q1_, v1_);
;             }
	v_mul_f32_e32 v26, v0, v26
	v_mul_f32_e32 v27, v1, v27
	v_mul_f32_e32 v28, v2, v28
	v_mul_f32_e32 v29, v3, v29
	v_mul_f32_e32 v30, v4, v30
	v_mul_f32_e32 v31, v5, v31
	v_mul_f32_e32 v32, v6, v32
	v_mul_f32_e32 v34, v7, v34
	v_add_f32_dpp v35, v35, v35 quad_perm:[2,3,0,1] row_mask:0xf bank_mask:0xf bound_ctrl:1
	ds_write_b32 v175, v35
	v_add_u32_e32 v175, v175, v162
	v_fmac_f32_e32 v26, v8, v33
	v_fmac_f32_e32 v27, v9, v33
	v_fmac_f32_e32 v28, v10, v33
	v_fmac_f32_e32 v29, v11, v33
	v_fmac_f32_e32 v30, v12, v33
	v_fmac_f32_e32 v31, v13, v33
	v_fmac_f32_e32 v32, v14, v33
	v_fmac_f32_e32 v34, v15, v33
	v_mul_f32_e32 v40, v16, v26
	v_mul_f32_e32 v41, v17, v27
	v_fmac_f32_e32 v40, v18, v28
	v_fmac_f32_e32 v41, v19, v29
	v_fmac_f32_e32 v40, v20, v30
	v_fmac_f32_e32 v41, v21, v31
	v_fmac_f32_e32 v40, v22, v32
	v_fmac_f32_e32 v41, v23, v34
	v_add_f32_e32 v35, v40, v41
	s_nop 1
	v_add_f32_dpp v35, v35, v35 quad_perm:[1,0,3,2] row_mask:0xf bank_mask:0xf bound_ctrl:1
	ds_read_b128 v[0:3], v24 offset:17024
	ds_read_b128 v[4:7], v24 offset:17040
	ds_read_b128 v[8:11], v24 offset:8832
	ds_read_b128 v[12:15], v24 offset:8848
	ds_read_b32 v33, v172 offset:25856
	ds_read_b128 v[16:19], v24 offset:640
	ds_read_b128 v[20:23], v24 offset:656
	s_waitcnt lgkmcnt(7)
	v_mul_f32_e32 v26, v176, v26
	v_mul_f32_e32 v27, v177, v27
	v_mul_f32_e32 v28, v178, v28
	v_mul_f32_e32 v29, v179, v29
	v_mul_f32_e32 v30, v180, v30
	v_mul_f32_e32 v31, v181, v31
	v_mul_f32_e32 v32, v182, v32
	v_mul_f32_e32 v34, v183, v34
	v_add_f32_dpp v35, v35, v35 quad_perm:[2,3,0,1] row_mask:0xf bank_mask:0xf bound_ctrl:1
	ds_write_b32 v175, v35
	v_add_u32_e32 v175, v175, v162
	v_fmac_f32_e32 v26, v184, v200
	v_fmac_f32_e32 v27, v185, v200
	v_fmac_f32_e32 v28, v186, v200
	v_fmac_f32_e32 v29, v187, v200
	v_fmac_f32_e32 v30, v188, v200
	v_fmac_f32_e32 v31, v189, v200
	v_fmac_f32_e32 v32, v190, v200
	v_fmac_f32_e32 v34, v191, v200
	v_mul_f32_e32 v40, v192, v26
	v_mul_f32_e32 v41, v193, v27
	v_fmac_f32_e32 v40, v194, v28
	v_fmac_f32_e32 v41, v195, v29
	v_fmac_f32_e32 v40, v196, v30
	v_fmac_f32_e32 v41, v197, v31
	v_fmac_f32_e32 v40, v198, v32
	v_fmac_f32_e32 v41, v199, v34
	v_add_f32_e32 v35, v40, v41
	s_nop 1
	v_add_f32_dpp v35, v35, v35 quad_perm:[1,0,3,2] row_mask:0xf bank_mask:0xf bound_ctrl:1
	ds_read_b128 v[176:179], v24 offset:17152
	ds_read_b128 v[180:183], v24 offset:17168
	ds_read_b128 v[184:187], v24 offset:8960
	ds_read_b128 v[188:191], v24 offset:8976
	ds_read_b32 v200, v172 offset:26112
	ds_read_b128 v[192:195], v24 offset:768
	ds_read_b128 v[196:199], v24 offset:784
	s_waitcnt lgkmcnt(7)
	v_mul_f32_e32 v26, v0, v26
	v_mul_f32_e32 v27, v1, v27
	v_mul_f32_e32 v28, v2, v28
	v_mul_f32_e32 v29, v3, v29
	v_mul_f32_e32 v30, v4, v30
	v_mul_f32_e32 v31, v5, v31
	v_mul_f32_e32 v32, v6, v32
	v_mul_f32_e32 v34, v7, v34
	v_add_f32_dpp v35, v35, v35 quad_perm:[2,3,0,1] row_mask:0xf bank_mask:0xf bound_ctrl:1
	ds_write_b32 v175, v35
	v_add_u32_e32 v175, v175, v162
	v_fmac_f32_e32 v26, v8, v33
	v_fmac_f32_e32 v27, v9, v33
	v_fmac_f32_e32 v28, v10, v33
	v_fmac_f32_e32 v29, v11, v33
	v_fmac_f32_e32 v30, v12, v33
	v_fmac_f32_e32 v31, v13, v33
	v_fmac_f32_e32 v32, v14, v33
	v_fmac_f32_e32 v34, v15, v33
	v_mul_f32_e32 v40, v16, v26
	v_mul_f32_e32 v41, v17, v27
	v_fmac_f32_e32 v40, v18, v28
	v_fmac_f32_e32 v41, v19, v29
	v_fmac_f32_e32 v40, v20, v30
	v_fmac_f32_e32 v41, v21, v31
	v_fmac_f32_e32 v40, v22, v32
	v_fmac_f32_e32 v41, v23, v34
	v_add_f32_e32 v35, v40, v41
	s_nop 1
	v_add_f32_dpp v35, v35, v35 quad_perm:[1,0,3,2] row_mask:0xf bank_mask:0xf bound_ctrl:1
	ds_read_b128 v[0:3], v24 offset:17280
	ds_read_b128 v[4:7], v24 offset:17296
	ds_read_b128 v[8:11], v24 offset:9088
	ds_read_b128 v[12:15], v24 offset:9104
	ds_read_b32 v33, v172 offset:26368
	ds_read_b128 v[16:19], v24 offset:896
	ds_read_b128 v[20:23], v24 offset:912
	s_waitcnt lgkmcnt(7)
	v_mul_f32_e32 v26, v176, v26
	v_mul_f32_e32 v27, v177, v27
	v_mul_f32_e32 v28, v178, v28
	v_mul_f32_e32 v29, v179, v29
	v_mul_f32_e32 v30, v180, v30
	v_mul_f32_e32 v31, v181, v31
	v_mul_f32_e32 v32, v182, v32
	v_mul_f32_e32 v34, v183, v34
	v_add_f32_dpp v35, v35, v35 quad_perm:[2,3,0,1] row_mask:0xf bank_mask:0xf bound_ctrl:1
	ds_write_b32 v175, v35
	v_add_u32_e32 v175, v175, v162
	v_fmac_f32_e32 v26, v184, v200
	v_fmac_f32_e32 v27, v185, v200
	v_fmac_f32_e32 v28, v186, v200
	v_fmac_f32_e32 v29, v187, v200
	v_fmac_f32_e32 v30, v188, v200
	v_fmac_f32_e32 v31, v189, v200
	v_fmac_f32_e32 v32, v190, v200
	v_fmac_f32_e32 v34, v191, v200
	v_mul_f32_e32 v40, v192, v26
	v_mul_f32_e32 v41, v193, v27
	v_fmac_f32_e32 v40, v194, v28
	v_fmac_f32_e32 v41, v195, v29
	v_fmac_f32_e32 v40, v196, v30
	v_fmac_f32_e32 v41, v197, v31
	v_fmac_f32_e32 v40, v198, v32
	v_fmac_f32_e32 v41, v199, v34
	v_add_f32_e32 v35, v40, v41
	s_nop 1
	v_add_f32_dpp v35, v35, v35 quad_perm:[1,0,3,2] row_mask:0xf bank_mask:0xf bound_ctrl:1
	ds_read_b128 v[176:179], v24 offset:17408
	ds_read_b128 v[180:183], v24 offset:17424
	ds_read_b128 v[184:187], v24 offset:9216
	ds_read_b128 v[188:191], v24 offset:9232
	ds_read_b32 v200, v172 offset:26624
	ds_read_b128 v[192:195], v24 offset:1024
	ds_read_b128 v[196:199], v24 offset:1040
	s_waitcnt lgkmcnt(7)
	v_mul_f32_e32 v26, v0, v26
	v_mul_f32_e32 v27, v1, v27
	v_mul_f32_e32 v28, v2, v28
	v_mul_f32_e32 v29, v3, v29
	v_mul_f32_e32 v30, v4, v30
	v_mul_f32_e32 v31, v5, v31
	v_mul_f32_e32 v32, v6, v32
	v_mul_f32_e32 v34, v7, v34
	v_add_f32_dpp v35, v35, v35 quad_perm:[2,3,0,1] row_mask:0xf bank_mask:0xf bound_ctrl:1
	ds_write_b32 v175, v35
	v_add_u32_e32 v175, v175, v162
	v_fmac_f32_e32 v26, v8, v33
	v_fmac_f32_e32 v27, v9, v33
	v_fmac_f32_e32 v28, v10, v33
	v_fmac_f32_e32 v29, v11, v33
	v_fmac_f32_e32 v30, v12, v33
	v_fmac_f32_e32 v31, v13, v33
	v_fmac_f32_e32 v32, v14, v33
	v_fmac_f32_e32 v34, v15, v33
	v_mul_f32_e32 v40, v16, v26
	v_mul_f32_e32 v41, v17, v27
	v_fmac_f32_e32 v40, v18, v28
	v_fmac_f32_e32 v41, v19, v29
	v_fmac_f32_e32 v40, v20, v30
	v_fmac_f32_e32 v41, v21, v31
	v_fmac_f32_e32 v40, v22, v32
	v_fmac_f32_e32 v41, v23, v34
	v_add_f32_e32 v35, v40, v41
	s_nop 1
	v_add_f32_dpp v35, v35, v35 quad_perm:[1,0,3,2] row_mask:0xf bank_mask:0xf bound_ctrl:1
	v_add_u32_e32 v24, 0x400, v24
	v_add_u32_e32 v172, 0x800, v172
	s_add_i32 s6, s6, 1
	s_cmp_lt_u32 s6, 7
	s_cbranch_scc1 .Lgla_rec_1047
; #define GLA_LD(t_, aq, kq, qq, vq) do { const int tt_ = (t_); vq = Bs[6144 + tt_ * 64 + pp]; \
;             _Pragma("unroll") for (int u = 0; u < 2; ++u) { aq[u] = *(const LAS f32x4*)(Bs + 4096 + tt_ * 32 + k0 + 4 * u); kq[u] = *(const LAS f32x4*)(Bs + 2048 + tt_ * 32 + k0 + 4 * u); qq[u] = *(const LAS f32x4*)(Bs + tt_ * 32 + k0 + 4 * u); } } while (0)
; #define GLA_STEP(t_, aq, kq, qq, vq) do { float y = 0.f; \
;             _Pragma("unroll") for (int u = 0; u < 2; ++u) _Pragma("unroll") for (int j = 0; j < 4; ++j) { S[4 * u + j] = aq[u][j] * S[4 * u + j] + kq[u][j] * vq; y += qq[u][j] * S[4 * u + j]; } \
;             y += dpp_f(y, 0xB1); y += dpp_f(y, 0x4E); ydst[(t_) * ystride] = y; } while (0)
; __device__ __forceinline__ void gla_job(const bf16_t* P, bf16_t* Y, int l, int b, int h, LAS float* lds, int wave_s) {
;     ...
;             GLA_LD(0, a0_, k0_, q0_, v0_);
;             for (int t = 0; t < TC; t += 2) {
;                 GLA_LD(t + 1, a1_, k1_, q1_, v1_);
;                 GLA_STEP(t, a0_, k0_, q0_, v0_);
;                 GLA_LD(t + 2 < TC ? t + 2 : t + 1, a0_, k0_, q0_, v0_);
;                 GLA_STEP(t + 1, a1_, k1_, q1_, v1_);
;             }
	ds_read_b128 v[0:3], v24 offset:16512
	ds_read_b128 v[4:7], v24 offset:16528
	ds_read_b128 v[8:11], v24 offset:8320
	ds_read_b128 v[12:15], v24 offset:8336
	ds_read_b32 v33, v172 offset:24832
	ds_read_b128 v[16:19], v24 offset:128
	ds_read_b128 v[20:23], v24 offset:144
	s_waitcnt lgkmcnt(7)
	v_mul_f32_e32 v26, v176, v26
	v_mul_f32_e32 v27, v177, v27
	v_mul_f32_e32 v28, v178, v28
	v_mul_f32_e32 v29, v179, v29
	v_mul_f32_e32 v30, v180, v30
	v_mul_f32_e32 v31, v181, v31
	v_mul_f32_e32 v32, v182, v32
	v_mul_f32_e32 v34, v183, v34
	v_add_f32_dpp v35, v35, v35 quad_perm:[2,3,0,1] row_mask:0xf bank_mask:0xf bound_ctrl:1
	ds_write_b32 v175, v35
	v_add_u32_e32 v175, v175, v162
	v_fmac_f32_e32 v26, v184, v200
	v_fmac_f32_e32 v27, v185, v200
	v_fmac_f32_e32 v28, v186, v200
	v_fmac_f32_e32 v29, v187, v200
	v_fmac_f32_e32 v30, v188, v200
	v_fmac_f32_e32 v31, v189, v200
	v_fmac_f32_e32 v32, v190, v200
	v_fmac_f32_e32 v34, v191, v200
	v_mul_f32_e32 v40, v192, v26
	v_mul_f32_e32 v41, v193, v27
	v_fmac_f32_e32 v40, v194, v28
	v_fmac_f32_e32 v41, v195, v29
	v_fmac_f32_e32 v40, v196, v30
	v_fmac_f32_e32 v41, v197, v31
	v_fmac_f32_e32 v40, v198, v32
	v_fmac_f32_e32 v41, v199, v34
	v_add_f32_e32 v35, v40, v41
	s_nop 1
	v_add_f32_dpp v35, v35, v35 quad_perm:[1,0,3,2] row_mask:0xf bank_mask:0xf bound_ctrl:1
	ds_read_b128 v[176:179], v24 offset:16640
	ds_read_b128 v[180:183], v24 offset:16656
	ds_read_b128 v[184:187], v24 offset:8448
	ds_read_b128 v[188:191], v24 offset:8464
	ds_read_b32 v200, v172 offset:25088
	ds_read_b128 v[192:195], v24 offset:256
	ds_read_b128 v[196:199], v24 offset:272
	s_waitcnt lgkmcnt(7)
	v_mul_f32_e32 v26, v0, v26
	v_mul_f32_e32 v27, v1, v27
	v_mul_f32_e32 v28, v2, v28
	v_mul_f32_e32 v29, v3, v29
	v_mul_f32_e32 v30, v4, v30
	v_mul_f32_e32 v31, v5, v31
	v_mul_f32_e32 v32, v6, v32
	v_mul_f32_e32 v34, v7, v34
	v_add_f32_dpp v35, v35, v35 quad_perm:[2,3,0,1] row_mask:0xf bank_mask:0xf bound_ctrl:1
	ds_write_b32 v175, v35
	v_add_u32_e32 v175, v175, v162
	v_fmac_f32_e32 v26, v8, v33
	v_fmac_f32_e32 v27, v9, v33
	v_fmac_f32_e32 v28, v10, v33
	v_fmac_f32_e32 v29, v11, v33
	v_fmac_f32_e32 v30, v12, v33
	v_fmac_f32_e32 v31, v13, v33
	v_fmac_f32_e32 v32, v14, v33
	v_fmac_f32_e32 v34, v15, v33
	v_mul_f32_e32 v40, v16, v26
	v_mul_f32_e32 v41, v17, v27
	v_fmac_f32_e32 v40, v18, v28
	v_fmac_f32_e32 v41, v19, v29
	v_fmac_f32_e32 v40, v20, v30
	v_fmac_f32_e32 v41, v21, v31
	v_fmac_f32_e32 v40, v22, v32
	v_fmac_f32_e32 v41, v23, v34
	v_add_f32_e32 v35, v40, v41
	s_nop 1
	v_add_f32_dpp v35, v35, v35 quad_perm:[1,0,3,2] row_mask:0xf bank_mask:0xf bound_ctrl:1
	ds_read_b128 v[0:3], v24 offset:16768
	ds_read_b128 v[4:7], v24 offset:16784
	ds_read_b128 v[8:11], v24 offset:8576
	ds_read_b128 v[12:15], v24 offset:8592
	ds_read_b32 v33, v172 offset:25344
	ds_read_b128 v[16:19], v24 offset:384
	ds_read_b128 v[20:23], v24 offset:400
	s_waitcnt lgkmcnt(7)
	v_mul_f32_e32 v26, v176, v26
	v_mul_f32_e32 v27, v177, v27
	v_mul_f32_e32 v28, v178, v28
	v_mul_f32_e32 v29, v179, v29
	v_mul_f32_e32 v30, v180, v30
	v_mul_f32_e32 v31, v181, v31
	v_mul_f32_e32 v32, v182, v32
	v_mul_f32_e32 v34, v183, v34
	v_add_f32_dpp v35, v35, v35 quad_perm:[2,3,0,1] row_mask:0xf bank_mask:0xf bound_ctrl:1
	ds_write_b32 v175, v35
	v_add_u32_e32 v175, v175, v162
	v_fmac_f32_e32 v26, v184, v200
	v_fmac_f32_e32 v27, v185, v200
	v_fmac_f32_e32 v28, v186, v200
	v_fmac_f32_e32 v29, v187, v200
	v_fmac_f32_e32 v30, v188, v200
	v_fmac_f32_e32 v31, v189, v200
	v_fmac_f32_e32 v32, v190, v200
	v_fmac_f32_e32 v34, v191, v200
	v_mul_f32_e32 v40, v192, v26
	v_mul_f32_e32 v41, v193, v27
	v_fmac_f32_e32 v40, v194, v28
	v_fmac_f32_e32 v41, v195, v29
	v_fmac_f32_e32 v40, v196, v30
	v_fmac_f32_e32 v41, v197, v31
	v_fmac_f32_e32 v40, v198, v32
	v_fmac_f32_e32 v41, v199, v34
	v_add_f32_e32 v35, v40, v41
	s_nop 1
	v_add_f32_dpp v35, v35, v35 quad_perm:[1,0,3,2] row_mask:0xf bank_mask:0xf bound_ctrl:1
	ds_read_b128 v[176:179], v24 offset:16896
	ds_read_b128 v[180:183], v24 offset:16912
	ds_read_b128 v[184:187], v24 offset:8704
	ds_read_b128 v[188:191], v24 offset:8720
	ds_read_b32 v200, v172 offset:25600
	ds_read_b128 v[192:195], v24 offset:512
	ds_read_b128 v[196:199], v24 offset:528
	s_waitcnt lgkmcnt(7)
; #define LAS __attribute__((address_space(3)))
; #define GLA_LD(t_, aq, kq, qq, vq) do { const int tt_ = (t_); vq = Bs[6144 + tt_ * 64 + pp]; \
;             _Pragma("unroll") for (int u = 0; u < 2; ++u) { aq[u] = *(const LAS f32x4*)(Bs + 4096 + tt_ * 32 + k0 + 4 * u); kq[u] = *(const LAS f32x4*)(Bs + 2048 + tt_ * 32 + k0 + 4 * u); qq[u] = *(const LAS f32x4*)(Bs + tt_ * 32 + k0 + 4 * u); } } while (0)
; #define GLA_STEP(t_, aq, kq, qq, vq) do { float y = 0.f; \
;             _Pragma("unroll") for (int u = 0; u < 2; ++u) _Pragma("unroll") for (int j = 0; j < 4; ++j) { S[4 * u + j] = aq[u][j] * S[4 * u + j] + kq[u][j] * vq; y += qq[u][j] * S[4 * u + j]; } \
;             y += dpp_f(y, 0xB1); y += dpp_f(y, 0x4E); ydst[(t_) * ystride] = y; } while (0)
; __device__ __forceinline__ void gla_job(const bf16_t* P, bf16_t* Y, int l, int b, int h, LAS float* lds, int wave_s) {
;     ...
;         if (wave_s < 4) {
;             LAS float* ydst = (lane & 3) == 0 ? (Yl + (c & 1) * 4096 + pp) : (lds + (LDS_XB + 256) / 4 + lane); const int ystride = (lane & 3) == 0 ? 64 : 0;
;             f32x4 a0_[2], k0_[2], q0_[2], a1_[2], k1_[2], q1_[2]; float v0_, v1_;
;     ...
;             GLA_LD(0, a0_, k0_, q0_, v0_);
;             for (int t = 0; t < TC; t += 2) {
;                 GLA_LD(t + 1, a1_, k1_, q1_, v1_);
;                 GLA_STEP(t, a0_, k0_, q0_, v0_);
;                 GLA_LD(t + 2 < TC ? t + 2 : t + 1, a0_, k0_, q0_, v0_);
;                 GLA_STEP(t + 1, a1_, k1_, q1_, v1_);
;             }
	v_mul_f32_e32 v26, v0, v26
	v_mul_f32_e32 v27, v1, v27
	v_mul_f32_e32 v28, v2, v28
	v_mul_f32_e32 v29, v3, v29
	v_mul_f32_e32 v30, v4, v30
	v_mul_f32_e32 v31, v5, v31
	v_mul_f32_e32 v32, v6, v32
	v_mul_f32_e32 v34, v7, v34
	v_add_f32_dpp v35, v35, v35 quad_perm:[2,3,0,1] row_mask:0xf bank_mask:0xf bound_ctrl:1
	ds_write_b32 v175, v35
	v_add_u32_e32 v175, v175, v162
	v_fmac_f32_e32 v26, v8, v33
	v_fmac_f32_e32 v27, v9, v33
	v_fmac_f32_e32 v28, v10, v33
	v_fmac_f32_e32 v29, v11, v33
	v_fmac_f32_e32 v30, v12, v33
	v_fmac_f32_e32 v31, v13, v33
	v_fmac_f32_e32 v32, v14, v33
	v_fmac_f32_e32 v34, v15, v33
	v_mul_f32_e32 v40, v16, v26
	v_mul_f32_e32 v41, v17, v27
	v_fmac_f32_e32 v40, v18, v28
	v_fmac_f32_e32 v41, v19, v29
	v_fmac_f32_e32 v40, v20, v30
	v_fmac_f32_e32 v41, v21, v31
	v_fmac_f32_e32 v40, v22, v32
	v_fmac_f32_e32 v41, v23, v34
	v_add_f32_e32 v35, v40, v41
	s_nop 1
	v_add_f32_dpp v35, v35, v35 quad_perm:[1,0,3,2] row_mask:0xf bank_mask:0xf bound_ctrl:1
	ds_read_b128 v[0:3], v24 offset:17024
	ds_read_b128 v[4:7], v24 offset:17040
	ds_read_b128 v[8:11], v24 offset:8832
	ds_read_b128 v[12:15], v24 offset:8848
	ds_read_b32 v33, v172 offset:25856
	ds_read_b128 v[16:19], v24 offset:640
	ds_read_b128 v[20:23], v24 offset:656
	s_waitcnt lgkmcnt(7)
	v_mul_f32_e32 v26, v176, v26
	v_mul_f32_e32 v27, v177, v27
	v_mul_f32_e32 v28, v178, v28
	v_mul_f32_e32 v29, v179, v29
	v_mul_f32_e32 v30, v180, v30
	v_mul_f32_e32 v31, v181, v31
	v_mul_f32_e32 v32, v182, v32
	v_mul_f32_e32 v34, v183, v34
	v_add_f32_dpp v35, v35, v35 quad_perm:[2,3,0,1] row_mask:0xf bank_mask:0xf bound_ctrl:1
	ds_write_b32 v175, v35
	v_add_u32_e32 v175, v175, v162
	v_fmac_f32_e32 v26, v184, v200
	v_fmac_f32_e32 v27, v185, v200
	v_fmac_f32_e32 v28, v186, v200
	v_fmac_f32_e32 v29, v187, v200
	v_fmac_f32_e32 v30, v188, v200
	v_fmac_f32_e32 v31, v189, v200
	v_fmac_f32_e32 v32, v190, v200
	v_fmac_f32_e32 v34, v191, v200
	v_mul_f32_e32 v40, v192, v26
	v_mul_f32_e32 v41, v193, v27
	v_fmac_f32_e32 v40, v194, v28
	v_fmac_f32_e32 v41, v195, v29
	v_fmac_f32_e32 v40, v196, v30
	v_fmac_f32_e32 v41, v197, v31
	v_fmac_f32_e32 v40, v198, v32
	v_fmac_f32_e32 v41, v199, v34
	v_add_f32_e32 v35, v40, v41
	s_nop 1
	v_add_f32_dpp v35, v35, v35 quad_perm:[1,0,3,2] row_mask:0xf bank_mask:0xf bound_ctrl:1
	ds_read_b128 v[176:179], v24 offset:17152
	ds_read_b128 v[180:183], v24 offset:17168
	ds_read_b128 v[184:187], v24 offset:8960
	ds_read_b128 v[188:191], v24 offset:8976
	ds_read_b32 v200, v172 offset:26112
	ds_read_b128 v[192:195], v24 offset:768
	ds_read_b128 v[196:199], v24 offset:784
	s_waitcnt lgkmcnt(7)
	v_mul_f32_e32 v26, v0, v26
	v_mul_f32_e32 v27, v1, v27
	v_mul_f32_e32 v28, v2, v28
	v_mul_f32_e32 v29, v3, v29
	v_mul_f32_e32 v30, v4, v30
	v_mul_f32_e32 v31, v5, v31
	v_mul_f32_e32 v32, v6, v32
	v_mul_f32_e32 v34, v7, v34
	v_add_f32_dpp v35, v35, v35 quad_perm:[2,3,0,1] row_mask:0xf bank_mask:0xf bound_ctrl:1
	ds_write_b32 v175, v35
	v_add_u32_e32 v175, v175, v162
	v_fmac_f32_e32 v26, v8, v33
	v_fmac_f32_e32 v27, v9, v33
	v_fmac_f32_e32 v28, v10, v33
	v_fmac_f32_e32 v29, v11, v33
	v_fmac_f32_e32 v30, v12, v33
	v_fmac_f32_e32 v31, v13, v33
	v_fmac_f32_e32 v32, v14, v33
	v_fmac_f32_e32 v34, v15, v33
	v_mul_f32_e32 v40, v16, v26
	v_mul_f32_e32 v41, v17, v27
	v_fmac_f32_e32 v40, v18, v28
	v_fmac_f32_e32 v41, v19, v29
	v_fmac_f32_e32 v40, v20, v30
	v_fmac_f32_e32 v41, v21, v31
	v_fmac_f32_e32 v40, v22, v32
	v_fmac_f32_e32 v41, v23, v34
	v_add_f32_e32 v35, v40, v41
	s_nop 1
	v_add_f32_dpp v35, v35, v35 quad_perm:[1,0,3,2] row_mask:0xf bank_mask:0xf bound_ctrl:1
	s_waitcnt lgkmcnt(1)
	v_mul_f32_e32 v26, v176, v26
	v_mul_f32_e32 v27, v177, v27
	v_mul_f32_e32 v28, v178, v28
	v_mul_f32_e32 v29, v179, v29
	v_mul_f32_e32 v30, v180, v30
	v_mul_f32_e32 v31, v181, v31
	v_mul_f32_e32 v32, v182, v32
	v_mul_f32_e32 v34, v183, v34
	v_add_f32_dpp v35, v35, v35 quad_perm:[2,3,0,1] row_mask:0xf bank_mask:0xf bound_ctrl:1
	ds_write_b32 v175, v35
	v_add_u32_e32 v175, v175, v162
	v_fmac_f32_e32 v26, v184, v200
	v_fmac_f32_e32 v27, v185, v200
	v_fmac_f32_e32 v28, v186, v200
	v_fmac_f32_e32 v29, v187, v200
	v_fmac_f32_e32 v30, v188, v200
	v_fmac_f32_e32 v31, v189, v200
	v_fmac_f32_e32 v32, v190, v200
	v_fmac_f32_e32 v34, v191, v200
	v_mul_f32_e32 v40, v192, v26
	v_mul_f32_e32 v41, v193, v27
	v_fmac_f32_e32 v40, v194, v28
	v_fmac_f32_e32 v41, v195, v29
	v_fmac_f32_e32 v40, v196, v30
	v_fmac_f32_e32 v41, v197, v31
	v_fmac_f32_e32 v40, v198, v32
	v_fmac_f32_e32 v41, v199, v34
	v_add_f32_e32 v35, v40, v41
	s_nop 1
	v_add_f32_dpp v35, v35, v35 quad_perm:[1,0,3,2] row_mask:0xf bank_mask:0xf bound_ctrl:1
	s_nop 1
	v_add_f32_dpp v35, v35, v35 quad_perm:[2,3,0,1] row_mask:0xf bank_mask:0xf bound_ctrl:1
	ds_write_b32 v175, v35
	s_setprio 0
	s_branch .LBB0_1037
